# speedup vs baseline: 1.0081x; 1.0002x over previous
; __device__ void phase4(const Params& p) {
;   char* ws = p.ws;
;   const u16* ya = (const u16*)((char*)p.out + OUT_OFF_XH);
;   const u16* yb = (const u16*)(ws + OFF_XB);
;   const u16* sga = (const u16*)(ws + OFF_SGA);
;   const u16* sgb = (const u16*)(ws + OFF_SGB);
;   u16* mo = (u16*)(ws + OFF_XA);
;   constexpr int nM = T / 256, nN = D / 256;
;   f32x4 acc[2][2][4][2];
;   for (int it = 0;; ++it) {
;     int pm, pn;
;     if (!tile_coords(it, nM, nN, pm, pn)) break;
;     const int to = pm * 256, fo = pn * 256;
;     EPI_COORDS
;     int nseg = 2;
;     asm volatile("" : "+s"(nseg));
.LBB0_590:
	s_or_b64 exec, exec, s[0:1]
	s_add_u32 s10, s30, 0x26000000
	s_addc_u32 s11, s31, 0
	s_add_u32 s12, s30, 0x30000000
	s_addc_u32 s13, s31, 0
	s_mov_b32 s1, 0
	s_movk_i32 s3, 0x60
	s_mov_b32 s17, 0x2900000
	v_mov_b32_e32 v1, 0
	s_mov_b32 s70, 0x10000
	s_mov_b32 s71, 0x14000
	s_mov_b64 s[6:7], 0x80
	s_mov_b32 s72, 0x18000
	s_mov_b32 s73, 0x1c000
	s_mov_b64 s[8:9], 0x100
	s_mov_b64 s[14:15], 0x180
	s_movk_i32 s76, 0x100
	s_mov_b32 s16, 0x3b808081
	v_mov_b32_e32 v148, 1
	s_mov_b32 s77, 0
	s_mov_b32 s100, 0
	s_barrier
	s_branch .LBB0_593

; __device__ __forceinline__ int otid() { int t = threadIdx.x; asm volatile("" : "+v"(t)); return t; }
; #define WAIT_V(n) asm volatile("s_waitcnt vmcnt(" #n ")" ::: "memory")
; #define BAR __builtin_amdgcn_s_barrier()
; __device__ __forceinline__ void gemm_tile(const u16* __restrict__ A, const u16* __restrict__ Bt, const int K,
;                                           const int brow, const int bcol, f32x4 (&acc)[2][2][4][2],
;                                           const bool ZERO_INIT = true) {
;     ...
;   const int tidx = otid();
;   const int wid = tidx >> 6, lane = tidx & 63, wr = wid >> 2, wc = wid & 3, fr = lane & 15, fq = lane >> 4;
;   #pragma unroll
;   for (int a = 0; a < 2; ++a)
;     #pragma unroll
;     for (int b = 0; b < 2; ++b)
;       #pragma unroll
;       for (int m = 0; m < 4; ++m)
;         #pragma unroll
;         for (int n = 0; n < 2; ++n)
;           if (ZERO_INIT) acc[a][b][m][n] = f32x4{0.f, 0.f, 0.f, 0.f};
;   bf16x8 At[4][2], B0[2][2], B1[2][2];
;   const int nt = K / BK;
;   const unsigned ldsw = (unsigned)__builtin_amdgcn_readfirstlane(wid) * 1024u;
;   unsigned vo0, vo1;
;   {
;     int r0, c0, r1, c1;
;     stage_rc(tidx * 16, r0, c0);
;     stage_rc(tidx * 16 + 8192, r1, c1);
;     vo0 = (unsigned)(r0 * K + c0) * 2u;
;     vo1 = (unsigned)(r1 * K + c1) * 2u;
;   }
;   STAGE(SB(0, 0), Bt, bcol, 0); STAGE(SA(0, 0), A, brow, 0);
;   STAGE(SB(0, 1), Bt, bcol + HALF, 0); STAGE(SA(0, 1), A, brow + HALF, 0);
;   if (wr == 1) BAR;
;   WAIT_V(4); BAR;
;   STAGE(SB(1, 0), Bt, bcol, 1); STAGE(SA(1, 0), A, brow, 1); STAGE(SB(1, 1), Bt, bcol + HALF, 1);
;   WAIT_V(6); BAR;
; __device__ void phase4(const Params& p) {
;     ...
;       const u16* Wp = (const u16*)(ws + (seg == 0 ? OFF_WA : OFF_WB));
;       const u16* Xp = seg == 0 ? ya : yb;
;       const int Kp = seg == 0 ? 2048 : 1024;
;       gemm_tile(Wp, Xp, Kp, fo, to, acc, seg == 0);
.LBB0_602:
	v_bfe_i32 v3, v151, 27, 1
	v_lshlrev_b32_e32 v0, 4, v151
	v_lshrrev_b32_e32 v3, 22, v3
	v_add_u32_e32 v3, v0, v3
	v_and_b32_e32 v3, 0xfffffc00, v3
	v_sub_u32_e32 v3, v0, v3
	v_lshrrev_b32_e32 v133, 4, v3
	v_bitop3_b32 v133, v133, v3, 32 bitop3:0x6c
	v_ashrrev_i32_e32 v3, 31, v3
	v_lshrrev_b32_e32 v3, 26, v3
	v_add_u32_e32 v3, v133, v3
	v_ashrrev_i32_e32 v3, 6, v3
	v_mul_i32_i24_e32 v135, 64, v3
	v_add_u32_e32 v0, 0x2000, v0
	v_sub_u32_e32 v133, v133, v135
	v_ashrrev_i32_e32 v135, 31, v0
	v_lshrrev_b32_e32 v135, 22, v135
	s_and_b64 s[24:25], s[52:53], exec
	v_add_u32_e32 v135, v0, v135
	s_cselect_b32 s89, s17, 0x3100000
	v_ashrrev_i32_e32 v135, 10, v135
	s_add_u32 s24, s30, s89
	v_mul_i32_i24_e32 v136, 0x400, v135
	s_addc_u32 s25, s31, 0
	v_sub_u32_e32 v0, v0, v136
	s_and_b64 s[54:55], s[52:53], exec
	v_ashrrev_i32_e32 v132, 6, v151
	v_lshrrev_b32_e32 v136, 4, v0
	s_cselect_b32 s90, s29, s45
	s_cselect_b32 s91, s28, s44
	v_readfirstlane_b32 s0, v132
	v_ashrrev_i32_e32 v2, 31, v151
	v_bitop3_b32 v0, v136, v0, 32 bitop3:0x6c
	s_lshl_b64 s[54:55], s[18:19], s50
	s_lshl_b32 s0, s0, 10
	v_lshrrev_b32_e32 v2, 26, v2
	v_ashrrev_i32_e32 v137, 31, v0
	s_lshl_b64 s[54:55], s[54:55], 1
	v_add_u32_e32 v2, v151, v2
	v_lshrrev_b32_e32 v137, 26, v137
	s_add_u32 s60, s91, s54
	v_ashrrev_i32_e32 v2, 6, v2
	v_add_u32_e32 v137, v0, v137
	s_addc_u32 s61, s90, s55
	s_lshl_b64 s[56:57], s[20:21], s50
	v_lshlrev_b32_e32 v134, 3, v2
	v_lshlrev_b32_e32 v2, 5, v2
	v_ashrrev_i32_e32 v138, 6, v137
	v_and_b32_e32 v137, 0xc0, v137
	s_add_i32 s80, s0, 0x10000
	s_add_i32 s81, s0, 0x12000
	s_lshl_b64 s[56:57], s[56:57], 1
	v_and_b32_e32 v134, 0x7ffffff0, v134
	v_and_b32_e32 v2, 32, v2
	v_ashrrev_i16_sdwa v133, v148, sext(v133) dst_sel:DWORD dst_unused:UNUSED_PAD src0_sel:DWORD src1_sel:BYTE_0
	v_lshlrev_b32_e32 v136, 3, v135
	v_lshlrev_b32_e32 v135, 5, v135
	v_sub_u32_e32 v0, v0, v137
	s_add_u32 s62, s24, s56
	v_and_b32_e32 v136, 0x7ffffff0, v136
	v_and_b32_e32 v135, 32, v135
	v_ashrrev_i16_sdwa v137, v148, sext(v0) dst_sel:DWORD dst_unused:UNUSED_PAD src0_sel:DWORD src1_sel:BYTE_0
	v_add_lshl_u32 v0, v3, v134, s50
	v_add_u32_sdwa v2, v2, sext(v133) dst_sel:DWORD dst_unused:UNUSED_PAD src0_sel:DWORD src1_sel:WORD_0
	s_addc_u32 s63, s25, s57
	s_lshl_b64 s[58:59], s[22:23], s50
	v_add_lshl_u32 v0, v2, v0, 1
	v_add_lshl_u32 v2, v138, v136, s50
	v_add_u32_sdwa v3, v135, sext(v137) dst_sel:DWORD dst_unused:UNUSED_PAD src0_sel:DWORD src1_sel:WORD_0
	s_add_i32 s82, s0, 0x2000
	s_lshl_b64 s[58:59], s[58:59], 1
	v_add_lshl_u32 v2, v3, v2, 1
	s_add_u32 s64, s91, s58
	s_addc_u32 s65, s90, s59
	s_lshl_b64 s[50:51], s[46:47], s50
	s_lshl_b64 s[50:51], s[50:51], 1
	s_add_u32 s66, s24, s50
	s_addc_u32 s67, s25, s51
	s_add_i32 s83, s0, 0x14000
	s_add_i32 s84, s0, 0x16000
	s_add_i32 s85, s0, 0x4000
	s_add_i32 s88, s0, 0x6000
	v_ashrrev_i32_e32 v133, 8, v151
	v_mov_b32_e32 v246, v0
	v_mov_b32_e32 v247, v2
	s_cmp_eq_u32 s100, 1
	s_cbranch_scc1 .Lp4_pf_skip
	s_mov_b32 m0, s80
	s_nop 0
	global_load_lds_dwordx4 v0, s[60:61]
	s_mov_b32 m0, s81
	s_nop 0
	global_load_lds_dwordx4 v2, s[60:61]
	s_mov_b32 m0, s0
	s_nop 0
	global_load_lds_dwordx4 v0, s[62:63]
	s_mov_b32 m0, s82
	s_nop 0
	global_load_lds_dwordx4 v2, s[62:63]
	s_mov_b32 m0, s83
	s_nop 0
	global_load_lds_dwordx4 v0, s[64:65]
	s_mov_b32 m0, s84
	s_nop 0
	global_load_lds_dwordx4 v2, s[64:65]
	s_mov_b32 m0, s85
	s_nop 0
	global_load_lds_dwordx4 v0, s[66:67]
	s_mov_b32 m0, s88
	s_nop 0
	global_load_lds_dwordx4 v2, s[66:67]
.Lp4_pf_skip:
	v_cmp_eq_u32_e32 vcc, 1, v133
	s_and_saveexec_b64 s[66:67], vcc
	s_cbranch_execz .LBB0_604
	s_barrier
.LBB0_604:
	s_or_b64 exec, exec, s[66:67]
	v_mov_b32_e32 v3, v1
	s_and_b64 s[52:53], s[52:53], exec
	v_lshl_add_u64 v[134:135], s[60:61], 0, v[0:1]
	v_lshl_add_u64 v[136:137], s[60:61], 0, v[2:3]
	s_cselect_b32 s60, 32, 16
	s_add_i32 s61, s0, 0x18000
	v_lshl_add_u64 v[138:139], s[62:63], 0, v[0:1]
	v_lshl_add_u64 v[140:141], s[62:63], 0, v[2:3]
	v_lshl_add_u64 v[134:135], v[134:135], 0, s[6:7]
	s_mov_b32 m0, s61
	s_add_i32 s62, s0, 0x1a000
	s_cmp_eq_u32 s100, 1
	s_cbranch_scc1 .Lp4_w1_pf
	s_waitcnt vmcnt(4)
	s_branch .Lp4_w1_done
.Lp4_w1_pf:
	s_waitcnt vmcnt(20)
.Lp4_w1_done:
	s_barrier
	global_load_lds_dwordx4 v[134:135], off
	v_lshl_add_u64 v[134:135], v[136:137], 0, s[6:7]
	s_mov_b32 m0, s62
	s_add_i32 s63, s0, 0x8000
	v_lshl_add_u64 v[142:143], s[64:65], 0, v[0:1]
	v_lshl_add_u64 v[144:145], s[64:65], 0, v[2:3]
	global_load_lds_dwordx4 v[134:135], off
	v_lshl_add_u64 v[134:135], v[138:139], 0, s[6:7]
	s_mov_b32 m0, s63
	s_add_i32 s64, s0, 0xa000
	global_load_lds_dwordx4 v[134:135], off
	v_lshl_add_u64 v[134:135], v[140:141], 0, s[6:7]
	s_mov_b32 m0, s64
	s_add_i32 s65, s0, 0x1c000
	global_load_lds_dwordx4 v[134:135], off
	v_lshl_add_u64 v[134:135], v[142:143], 0, s[6:7]
	s_mov_b32 m0, s65
	s_add_i32 s66, s0, 0x1e000
	global_load_lds_dwordx4 v[134:135], off
	v_lshl_add_u64 v[134:135], v[144:145], 0, s[6:7]
	s_mov_b32 m0, s66
	v_lshlrev_b32_e32 v132, 12, v132
	global_load_lds_dwordx4 v[134:135], off
	v_and_b32_e32 v134, 15, v151
	v_lshlrev_b32_e32 v136, 2, v151
	v_and_b32_e32 v135, 48, v151
	s_add_i32 s67, s60, -2
	v_and_b32_e32 v156, 0x3000, v132
	v_lshlrev_b32_e32 v132, 6, v134
	v_and_b32_e32 v136, 32, v136
	v_or_b32_e32 v134, v132, v135
	v_bitop3_b32 v152, v132, v136, v135 bitop3:0x36
	v_lshlrev_b32_e32 v132, 6, v151
	s_add_u32 s52, s91, s58
	v_and_b32_e32 v132, 0x3c0, v132
	s_addc_u32 s53, s90, s59
	v_bitop3_b32 v153, v134, s70, v136 bitop3:0xde
	v_bitop3_b32 v157, v134, s71, v136 bitop3:0xde
	v_bitop3_b32 v160, v134, s72, v136 bitop3:0xde
	v_bitop3_b32 v161, v134, s73, v136 bitop3:0xde
	v_lshlrev_b32_e32 v154, 13, v133
	v_bitop3_b32 v158, v132, v136, v135 bitop3:0x36
	v_lshl_add_u64 v[132:133], s[52:53], 0, v[0:1]
	v_lshl_add_u64 v[134:135], s[52:53], 0, v[2:3]
	s_add_u32 s52, s89, s56
	s_addc_u32 s53, 0, s57
	s_add_u32 s52, s30, s52
	s_addc_u32 s53, s31, s53
	v_lshl_add_u64 v[136:137], s[52:53], 0, v[0:1]
	v_lshl_add_u64 v[138:139], s[52:53], 0, v[2:3]
	s_add_u32 s52, s91, s54
	s_addc_u32 s53, s90, s55
	v_lshl_add_u64 v[140:141], s[52:53], 0, v[0:1]
	v_lshl_add_u64 v[142:143], s[52:53], 0, v[2:3]
	s_add_u32 s52, s89, s50
	s_addc_u32 s53, 0, s51
	s_cmp_eq_u32 s100, 1
	s_cbranch_scc1 .Lp4_w2_pf
	s_waitcnt vmcnt(6)
	s_branch .Lp4_w2_done
.Lp4_w2_pf:
	s_waitcnt vmcnt(22)
.Lp4_w2_done:
	s_add_u32 s52, s30, s52
	v_or_b32_e32 v162, 0x800, v154
	v_or_b32_e32 v163, 0x1000, v154
	v_or_b32_e32 v164, 0x1800, v154
	s_addc_u32 s53, s31, s53
	v_lshl_add_u64 v[144:145], s[52:53], 0, v[0:1]
	v_lshl_add_u64 v[146:147], s[52:53], 0, v[2:3]
	s_mov_b32 s55, 0
	s_mov_b64 s[52:53], 0
	s_add_i32 s56, s0, 0xc000
	s_add_i32 s54, s0, 0xe000
	v_add_u32_e32 v159, v153, v156
	v_add_u32_e32 v155, v152, v154
	v_add_u32_e32 v154, v158, v162
	v_add_u32_e32 v153, v158, v163
	v_add_u32_e32 v152, v158, v164
	v_add_u32_e32 v158, v157, v156
	v_add_u32_e32 v157, v160, v156
	v_add_u32_e32 v156, v161, v156
	s_barrier

; __device__ __forceinline__ float u8f(unsigned w, int i) { return (float)((w >> (8 * i)) & 0xffu) * (1.f / 255.f); }
; #define EPI_BEGIN_S int fo_e = fo, to_e = to; asm volatile("" : "+s"(fo_e), "+s"(to_e));
; __device__ void phase4(const Params& p) {
;     ...
;       const u16* Wp = (const u16*)(ws + (seg == 0 ? OFF_WA : OFF_WB));
;       const u16* Xp = seg == 0 ? ya : yb;
;       const int Kp = seg == 0 ? 2048 : 1024;
;       gemm_tile(Wp, Xp, Kp, fo, to, acc, seg == 0);
;       EPI_BEGIN_S
;       const size_t lanef = (size_t)(fo_e + wr * 64 + fq * 4);
;       if (seg == 0) {
;         #pragma unroll
;         for (int bj = 0; bj < 2; ++bj)
;           #pragma unroll
;           for (int n = 0; n < 2; ++n) {
;             const size_t base = (size_t)EPI_T(bj, n) * D + lanef;
;             const unsigned* pa = reinterpret_cast<const unsigned*>(reinterpret_cast<const unsigned char*>(sga) + base);
;             const unsigned* pb = reinterpret_cast<const unsigned*>(reinterpret_cast<const unsigned char*>(sgb) + base);
;             #pragma unroll
;             for (int ai = 0; ai < 2; ++ai)
;               #pragma unroll
;               for (int m = 0; m < 4; ++m) {
;                 const unsigned ga = pa[(ai * 128 + m * 16) / 4];
;                 const unsigned gb = pb[(ai * 128 + m * 16) / 4];
;                 #pragma unroll
;                 for (int j = 0; j < 4; ++j)
;                   acc[ai][bj][m][n][j] *= u8f(ga, j) * __builtin_amdgcn_rcpf(fmaxf(u8f(gb, j), 1e-30f));
;               }
;             asm volatile("" ::: "memory");
;           }
.LBB0_608:
	s_or_b64 exec, exec, s[50:51]
	v_and_b32_e32 v132, 15, v194
	v_lshrrev_b32_e32 v133, 1, v194
	v_and_b32_e32 v133, 0x60, v133
	v_add3_u32 v132, s18, v132, v133
	v_bfe_u32 v134, v194, 4, 2
	v_lshrrev_b32_e32 v135, 2, v194
	v_and_b32_e32 v135, 0xffffffc0, v135
	v_lshl_add_u32 v136, v134, 4, v135
	v_add_u32_e32 v136, s20, v136
	v_lshl_add_u32 v136, v132, 11, v136
	v_add_u32_e32 v137, 0x8000, v136
	v_add_u32_e32 v138, 0x40000, v136
	v_add_u32_e32 v139, 0x48000, v136
	s_cmp_lg_u32 s79, 0
	s_cbranch_scc1 .Lp4e_seg1
	v_lshrrev_b32_e32 v248, 1, v246
	v_lshrrev_b32_e32 v250, 11, v248
	v_and_b32_e32 v248, 0x7ff, v248
	v_lshl_add_u32 v248, v250, 10, v248
	v_lshlrev_b32_e32 v250, 1, v248
	v_lshrrev_b32_e32 v249, 1, v247
	v_lshrrev_b32_e32 v251, 11, v249
	v_and_b32_e32 v249, 0x7ff, v249
	v_lshl_add_u32 v249, v251, 10, v249
	v_lshlrev_b32_e32 v251, 1, v249
	s_lshl_b32 s54, s18, 11
	s_add_u32 s58, s44, s54
	s_addc_u32 s59, s45, 0
	s_or_b32 s55, s18, 0x80
	s_lshl_b32 s55, s55, 11
	s_add_u32 s60, s44, s55
	s_addc_u32 s61, s45, 0
	s_lshl_b32 s54, s20, 11
	s_add_u32 s54, s54, 0x3100000
	s_add_u32 s62, s30, s54
	s_addc_u32 s63, s31, 0
	s_or_b32 s55, s20, 0x80
	s_lshl_b32 s55, s55, 11
	s_add_u32 s55, s55, 0x3100000
	s_add_u32 s64, s30, s55
	s_addc_u32 s65, s31, 0
	v_lshrrev_b32_e32 v252, 6, v194
	s_nop 0
	v_readfirstlane_b32 s66, v252
	s_lshl_b32 s66, s66, 10
	s_add_u32 m0, s66, 0x10000
	s_nop 0
	global_load_lds_dwordx4 v250, s[58:59]
	s_add_u32 m0, s66, 0x12000
	s_nop 0
	global_load_lds_dwordx4 v251, s[58:59]
	s_add_u32 m0, s66, 0x0
	s_nop 0
	global_load_lds_dwordx4 v250, s[62:63]
	s_add_u32 m0, s66, 0x2000
	s_nop 0
	global_load_lds_dwordx4 v251, s[62:63]
	s_add_u32 m0, s66, 0x14000
	s_nop 0
	global_load_lds_dwordx4 v250, s[60:61]
	s_add_u32 m0, s66, 0x16000
	s_nop 0
	global_load_lds_dwordx4 v251, s[60:61]
	s_add_u32 m0, s66, 0x4000
	s_nop 0
	global_load_lds_dwordx4 v250, s[64:65]
	s_add_u32 m0, s66, 0x6000
	s_nop 0
	global_load_lds_dwordx4 v251, s[64:65]
	s_mov_b32 s100, 1
	global_load_dwordx4 v[152:155], v136, s[10:11]
	global_load_dwordx4 v[156:159], v136, s[12:13]
	global_load_dwordx4 v[160:163], v136, s[10:11] offset:128
	global_load_dwordx4 v[164:167], v136, s[12:13] offset:128
	global_load_dwordx4 v[168:171], v137, s[10:11]
	global_load_dwordx4 v[172:175], v137, s[12:13]
	global_load_dwordx4 v[176:179], v137, s[10:11] offset:128
	global_load_dwordx4 v[180:183], v137, s[12:13] offset:128
	global_load_dwordx4 v[184:187], v138, s[10:11]
	global_load_dwordx4 v[188:191], v138, s[12:13]
	global_load_dwordx4 v[196:199], v138, s[10:11] offset:128
	global_load_dwordx4 v[200:203], v138, s[12:13] offset:128
	global_load_dwordx4 v[204:207], v139, s[10:11]
	global_load_dwordx4 v[208:211], v139, s[12:13]
	global_load_dwordx4 v[212:215], v139, s[10:11] offset:128
	global_load_dwordx4 v[216:219], v139, s[12:13] offset:128
	s_waitcnt vmcnt(14)
	v_permlane16_swap_b32 v152, v153
	v_permlane16_swap_b32 v154, v155
	v_permlane16_swap_b32 v156, v157
	v_permlane16_swap_b32 v158, v159
	v_permlane32_swap_b32 v152, v154
	v_permlane32_swap_b32 v153, v155
	v_permlane32_swap_b32 v156, v158
	v_permlane32_swap_b32 v157, v159
	v_cvt_f32_ubyte0_e32 v144, v156
	v_cvt_f32_ubyte1_e32 v145, v156
	v_cvt_f32_ubyte2_e32 v146, v156
	v_cvt_f32_ubyte3_e32 v147, v156
	v_cvt_f32_ubyte0_e32 v140, v152
	v_cvt_f32_ubyte1_e32 v141, v152
	v_cvt_f32_ubyte2_e32 v142, v152
	v_cvt_f32_ubyte3_e32 v143, v152
	v_pk_mul_f32 v[144:145], v[144:145], s[16:17] op_sel_hi:[1,0]
	v_pk_mul_f32 v[146:147], v[146:147], s[16:17] op_sel_hi:[1,0]
	v_pk_mul_f32 v[140:141], v[140:141], s[16:17] op_sel_hi:[1,0]
	v_pk_mul_f32 v[142:143], v[142:143], s[16:17] op_sel_hi:[1,0]
	v_max_f32_e32 v144, 0xda24260, v144
	v_max_f32_e32 v145, 0xda24260, v145
	v_max_f32_e32 v146, 0xda24260, v146
	v_max_f32_e32 v147, 0xda24260, v147
	v_rcp_f32_e32 v144, v144
	v_rcp_f32_e32 v145, v145
	v_rcp_f32_e32 v146, v146
	v_rcp_f32_e32 v147, v147
	v_pk_mul_f32 v[140:141], v[140:141], v[144:145]
	v_pk_mul_f32 v[142:143], v[142:143], v[146:147]
	v_pk_mul_f32 v[128:129], v[128:129], v[140:141]
	v_pk_mul_f32 v[130:131], v[130:131], v[142:143]
	v_cvt_f32_ubyte0_e32 v144, v157
	v_cvt_f32_ubyte1_e32 v145, v157
	v_cvt_f32_ubyte2_e32 v146, v157
	v_cvt_f32_ubyte3_e32 v147, v157
	v_cvt_f32_ubyte0_e32 v140, v153
	v_cvt_f32_ubyte1_e32 v141, v153
	v_cvt_f32_ubyte2_e32 v142, v153
	v_cvt_f32_ubyte3_e32 v143, v153
	v_pk_mul_f32 v[144:145], v[144:145], s[16:17] op_sel_hi:[1,0]
	v_pk_mul_f32 v[146:147], v[146:147], s[16:17] op_sel_hi:[1,0]
	v_pk_mul_f32 v[140:141], v[140:141], s[16:17] op_sel_hi:[1,0]
	v_pk_mul_f32 v[142:143], v[142:143], s[16:17] op_sel_hi:[1,0]
	v_max_f32_e32 v144, 0xda24260, v144
	v_max_f32_e32 v145, 0xda24260, v145
	v_max_f32_e32 v146, 0xda24260, v146
	v_max_f32_e32 v147, 0xda24260, v147
	v_rcp_f32_e32 v144, v144
	v_rcp_f32_e32 v145, v145
	v_rcp_f32_e32 v146, v146
	v_rcp_f32_e32 v147, v147
	v_pk_mul_f32 v[140:141], v[140:141], v[144:145]
	v_pk_mul_f32 v[142:143], v[142:143], v[146:147]
	v_pk_mul_f32 v[120:121], v[120:121], v[140:141]
	v_pk_mul_f32 v[122:123], v[122:123], v[142:143]
	v_cvt_f32_ubyte0_e32 v144, v158
	v_cvt_f32_ubyte1_e32 v145, v158
	v_cvt_f32_ubyte2_e32 v146, v158
	v_cvt_f32_ubyte3_e32 v147, v158
	v_cvt_f32_ubyte0_e32 v140, v154
	v_cvt_f32_ubyte1_e32 v141, v154
	v_cvt_f32_ubyte2_e32 v142, v154
	v_cvt_f32_ubyte3_e32 v143, v154
	v_pk_mul_f32 v[144:145], v[144:145], s[16:17] op_sel_hi:[1,0]
	v_pk_mul_f32 v[146:147], v[146:147], s[16:17] op_sel_hi:[1,0]
	v_pk_mul_f32 v[140:141], v[140:141], s[16:17] op_sel_hi:[1,0]
	v_pk_mul_f32 v[142:143], v[142:143], s[16:17] op_sel_hi:[1,0]
	v_max_f32_e32 v144, 0xda24260, v144
	v_max_f32_e32 v145, 0xda24260, v145
	v_max_f32_e32 v146, 0xda24260, v146
	v_max_f32_e32 v147, 0xda24260, v147
	v_rcp_f32_e32 v144, v144
	v_rcp_f32_e32 v145, v145
	v_rcp_f32_e32 v146, v146
	v_rcp_f32_e32 v147, v147
	v_pk_mul_f32 v[140:141], v[140:141], v[144:145]
	v_pk_mul_f32 v[142:143], v[142:143], v[146:147]
	v_pk_mul_f32 v[112:113], v[112:113], v[140:141]
	v_pk_mul_f32 v[114:115], v[114:115], v[142:143]
	v_cvt_f32_ubyte0_e32 v144, v159
	v_cvt_f32_ubyte1_e32 v145, v159
	v_cvt_f32_ubyte2_e32 v146, v159
	v_cvt_f32_ubyte3_e32 v147, v159
	v_cvt_f32_ubyte0_e32 v140, v155
	v_cvt_f32_ubyte1_e32 v141, v155
	v_cvt_f32_ubyte2_e32 v142, v155
	v_cvt_f32_ubyte3_e32 v143, v155
	v_pk_mul_f32 v[144:145], v[144:145], s[16:17] op_sel_hi:[1,0]
	v_pk_mul_f32 v[146:147], v[146:147], s[16:17] op_sel_hi:[1,0]
	v_pk_mul_f32 v[140:141], v[140:141], s[16:17] op_sel_hi:[1,0]
	v_pk_mul_f32 v[142:143], v[142:143], s[16:17] op_sel_hi:[1,0]
	v_max_f32_e32 v144, 0xda24260, v144
	v_max_f32_e32 v145, 0xda24260, v145
	v_max_f32_e32 v146, 0xda24260, v146
	v_max_f32_e32 v147, 0xda24260, v147
	v_rcp_f32_e32 v144, v144
	v_rcp_f32_e32 v145, v145
	v_rcp_f32_e32 v146, v146
	v_rcp_f32_e32 v147, v147
	v_pk_mul_f32 v[140:141], v[140:141], v[144:145]
	v_pk_mul_f32 v[142:143], v[142:143], v[146:147]
	v_pk_mul_f32 v[104:105], v[104:105], v[140:141]
	v_pk_mul_f32 v[106:107], v[106:107], v[142:143]
	s_waitcnt vmcnt(12)
; __device__ __forceinline__ float u8f(unsigned w, int i) { return (float)((w >> (8 * i)) & 0xffu) * (1.f / 255.f); }
; __device__ void phase4(const Params& p) {
;     ...
;       if (seg == 0) {
;         #pragma unroll
;         for (int bj = 0; bj < 2; ++bj)
;           #pragma unroll
;           for (int n = 0; n < 2; ++n) {
;             const size_t base = (size_t)EPI_T(bj, n) * D + lanef;
;             const unsigned* pa = reinterpret_cast<const unsigned*>(reinterpret_cast<const unsigned char*>(sga) + base);
;             const unsigned* pb = reinterpret_cast<const unsigned*>(reinterpret_cast<const unsigned char*>(sgb) + base);
;             #pragma unroll
;             for (int ai = 0; ai < 2; ++ai)
;               #pragma unroll
;               for (int m = 0; m < 4; ++m) {
;                 const unsigned ga = pa[(ai * 128 + m * 16) / 4];
;                 const unsigned gb = pb[(ai * 128 + m * 16) / 4];
;                 #pragma unroll
;                 for (int j = 0; j < 4; ++j)
;                   acc[ai][bj][m][n][j] *= u8f(ga, j) * __builtin_amdgcn_rcpf(fmaxf(u8f(gb, j), 1e-30f));
;               }
;             asm volatile("" ::: "memory");
;           }
	v_permlane16_swap_b32 v160, v161
	v_permlane16_swap_b32 v162, v163
	v_permlane16_swap_b32 v164, v165
	v_permlane16_swap_b32 v166, v167
	v_permlane32_swap_b32 v160, v162
	v_permlane32_swap_b32 v161, v163
	v_permlane32_swap_b32 v164, v166
	v_permlane32_swap_b32 v165, v167
	v_cvt_f32_ubyte0_e32 v144, v164
	v_cvt_f32_ubyte1_e32 v145, v164
	v_cvt_f32_ubyte2_e32 v146, v164
	v_cvt_f32_ubyte3_e32 v147, v164
	v_cvt_f32_ubyte0_e32 v140, v160
	v_cvt_f32_ubyte1_e32 v141, v160
	v_cvt_f32_ubyte2_e32 v142, v160
	v_cvt_f32_ubyte3_e32 v143, v160
	v_pk_mul_f32 v[144:145], v[144:145], s[16:17] op_sel_hi:[1,0]
	v_pk_mul_f32 v[146:147], v[146:147], s[16:17] op_sel_hi:[1,0]
	v_pk_mul_f32 v[140:141], v[140:141], s[16:17] op_sel_hi:[1,0]
	v_pk_mul_f32 v[142:143], v[142:143], s[16:17] op_sel_hi:[1,0]
	v_max_f32_e32 v144, 0xda24260, v144
	v_max_f32_e32 v145, 0xda24260, v145
	v_max_f32_e32 v146, 0xda24260, v146
	v_max_f32_e32 v147, 0xda24260, v147
	v_rcp_f32_e32 v144, v144
	v_rcp_f32_e32 v145, v145
	v_rcp_f32_e32 v146, v146
	v_rcp_f32_e32 v147, v147
	v_pk_mul_f32 v[140:141], v[140:141], v[144:145]
	v_pk_mul_f32 v[142:143], v[142:143], v[146:147]
	v_pk_mul_f32 v[64:65], v[64:65], v[140:141]
	v_pk_mul_f32 v[66:67], v[66:67], v[142:143]
	v_cvt_f32_ubyte0_e32 v144, v165
	v_cvt_f32_ubyte1_e32 v145, v165
	v_cvt_f32_ubyte2_e32 v146, v165
	v_cvt_f32_ubyte3_e32 v147, v165
	v_cvt_f32_ubyte0_e32 v140, v161
	v_cvt_f32_ubyte1_e32 v141, v161
	v_cvt_f32_ubyte2_e32 v142, v161
	v_cvt_f32_ubyte3_e32 v143, v161
	v_pk_mul_f32 v[144:145], v[144:145], s[16:17] op_sel_hi:[1,0]
	v_pk_mul_f32 v[146:147], v[146:147], s[16:17] op_sel_hi:[1,0]
	v_pk_mul_f32 v[140:141], v[140:141], s[16:17] op_sel_hi:[1,0]
	v_pk_mul_f32 v[142:143], v[142:143], s[16:17] op_sel_hi:[1,0]
	v_max_f32_e32 v144, 0xda24260, v144
	v_max_f32_e32 v145, 0xda24260, v145
	v_max_f32_e32 v146, 0xda24260, v146
	v_max_f32_e32 v147, 0xda24260, v147
	v_rcp_f32_e32 v144, v144
	v_rcp_f32_e32 v145, v145
	v_rcp_f32_e32 v146, v146
	v_rcp_f32_e32 v147, v147
	v_pk_mul_f32 v[140:141], v[140:141], v[144:145]
	v_pk_mul_f32 v[142:143], v[142:143], v[146:147]
	v_pk_mul_f32 v[56:57], v[56:57], v[140:141]
	v_pk_mul_f32 v[58:59], v[58:59], v[142:143]
	v_cvt_f32_ubyte0_e32 v144, v166
	v_cvt_f32_ubyte1_e32 v145, v166
	v_cvt_f32_ubyte2_e32 v146, v166
	v_cvt_f32_ubyte3_e32 v147, v166
	v_cvt_f32_ubyte0_e32 v140, v162
	v_cvt_f32_ubyte1_e32 v141, v162
	v_cvt_f32_ubyte2_e32 v142, v162
	v_cvt_f32_ubyte3_e32 v143, v162
	v_pk_mul_f32 v[144:145], v[144:145], s[16:17] op_sel_hi:[1,0]
	v_pk_mul_f32 v[146:147], v[146:147], s[16:17] op_sel_hi:[1,0]
	v_pk_mul_f32 v[140:141], v[140:141], s[16:17] op_sel_hi:[1,0]
	v_pk_mul_f32 v[142:143], v[142:143], s[16:17] op_sel_hi:[1,0]
	v_max_f32_e32 v144, 0xda24260, v144
	v_max_f32_e32 v145, 0xda24260, v145
	v_max_f32_e32 v146, 0xda24260, v146
	v_max_f32_e32 v147, 0xda24260, v147
	v_rcp_f32_e32 v144, v144
	v_rcp_f32_e32 v145, v145
	v_rcp_f32_e32 v146, v146
	v_rcp_f32_e32 v147, v147
	v_pk_mul_f32 v[140:141], v[140:141], v[144:145]
	v_pk_mul_f32 v[142:143], v[142:143], v[146:147]
	v_pk_mul_f32 v[48:49], v[48:49], v[140:141]
	v_pk_mul_f32 v[50:51], v[50:51], v[142:143]
	v_cvt_f32_ubyte0_e32 v144, v167
	v_cvt_f32_ubyte1_e32 v145, v167
	v_cvt_f32_ubyte2_e32 v146, v167
	v_cvt_f32_ubyte3_e32 v147, v167
	v_cvt_f32_ubyte0_e32 v140, v163
	v_cvt_f32_ubyte1_e32 v141, v163
	v_cvt_f32_ubyte2_e32 v142, v163
	v_cvt_f32_ubyte3_e32 v143, v163
	v_pk_mul_f32 v[144:145], v[144:145], s[16:17] op_sel_hi:[1,0]
	v_pk_mul_f32 v[146:147], v[146:147], s[16:17] op_sel_hi:[1,0]
	v_pk_mul_f32 v[140:141], v[140:141], s[16:17] op_sel_hi:[1,0]
	v_pk_mul_f32 v[142:143], v[142:143], s[16:17] op_sel_hi:[1,0]
	v_max_f32_e32 v144, 0xda24260, v144
	v_max_f32_e32 v145, 0xda24260, v145
	v_max_f32_e32 v146, 0xda24260, v146
	v_max_f32_e32 v147, 0xda24260, v147
	v_rcp_f32_e32 v144, v144
	v_rcp_f32_e32 v145, v145
	v_rcp_f32_e32 v146, v146
	v_rcp_f32_e32 v147, v147
	v_pk_mul_f32 v[140:141], v[140:141], v[144:145]
	v_pk_mul_f32 v[142:143], v[142:143], v[146:147]
	v_pk_mul_f32 v[40:41], v[40:41], v[140:141]
	v_pk_mul_f32 v[42:43], v[42:43], v[142:143]
	s_waitcnt vmcnt(10)
	v_permlane16_swap_b32 v168, v169
	v_permlane16_swap_b32 v170, v171
	v_permlane16_swap_b32 v172, v173
	v_permlane16_swap_b32 v174, v175
	v_permlane32_swap_b32 v168, v170
	v_permlane32_swap_b32 v169, v171
	v_permlane32_swap_b32 v172, v174
	v_permlane32_swap_b32 v173, v175
	v_cvt_f32_ubyte0_e32 v144, v172
	v_cvt_f32_ubyte1_e32 v145, v172
	v_cvt_f32_ubyte2_e32 v146, v172
	v_cvt_f32_ubyte3_e32 v147, v172
	v_cvt_f32_ubyte0_e32 v140, v168
	v_cvt_f32_ubyte1_e32 v141, v168
	v_cvt_f32_ubyte2_e32 v142, v168
	v_cvt_f32_ubyte3_e32 v143, v168
	v_pk_mul_f32 v[144:145], v[144:145], s[16:17] op_sel_hi:[1,0]
	v_pk_mul_f32 v[146:147], v[146:147], s[16:17] op_sel_hi:[1,0]
	v_pk_mul_f32 v[140:141], v[140:141], s[16:17] op_sel_hi:[1,0]
	v_pk_mul_f32 v[142:143], v[142:143], s[16:17] op_sel_hi:[1,0]
	v_max_f32_e32 v144, 0xda24260, v144
	v_max_f32_e32 v145, 0xda24260, v145
	v_max_f32_e32 v146, 0xda24260, v146
	v_max_f32_e32 v147, 0xda24260, v147
	v_rcp_f32_e32 v144, v144
	v_rcp_f32_e32 v145, v145
	v_rcp_f32_e32 v146, v146
	v_rcp_f32_e32 v147, v147
	v_pk_mul_f32 v[140:141], v[140:141], v[144:145]
	v_pk_mul_f32 v[142:143], v[142:143], v[146:147]
	v_pk_mul_f32 v[124:125], v[124:125], v[140:141]
	v_pk_mul_f32 v[126:127], v[126:127], v[142:143]
	v_cvt_f32_ubyte0_e32 v144, v173
	v_cvt_f32_ubyte1_e32 v145, v173
	v_cvt_f32_ubyte2_e32 v146, v173
	v_cvt_f32_ubyte3_e32 v147, v173
	v_cvt_f32_ubyte0_e32 v140, v169
	v_cvt_f32_ubyte1_e32 v141, v169
	v_cvt_f32_ubyte2_e32 v142, v169
	v_cvt_f32_ubyte3_e32 v143, v169
; __device__ __forceinline__ float u8f(unsigned w, int i) { return (float)((w >> (8 * i)) & 0xffu) * (1.f / 255.f); }
; __device__ void phase4(const Params& p) {
;     ...
;       if (seg == 0) {
;         #pragma unroll
;         for (int bj = 0; bj < 2; ++bj)
;           #pragma unroll
;           for (int n = 0; n < 2; ++n) {
;             const size_t base = (size_t)EPI_T(bj, n) * D + lanef;
;             const unsigned* pa = reinterpret_cast<const unsigned*>(reinterpret_cast<const unsigned char*>(sga) + base);
;             const unsigned* pb = reinterpret_cast<const unsigned*>(reinterpret_cast<const unsigned char*>(sgb) + base);
;             #pragma unroll
;             for (int ai = 0; ai < 2; ++ai)
;               #pragma unroll
;               for (int m = 0; m < 4; ++m) {
;                 const unsigned ga = pa[(ai * 128 + m * 16) / 4];
;                 const unsigned gb = pb[(ai * 128 + m * 16) / 4];
;                 #pragma unroll
;                 for (int j = 0; j < 4; ++j)
;                   acc[ai][bj][m][n][j] *= u8f(ga, j) * __builtin_amdgcn_rcpf(fmaxf(u8f(gb, j), 1e-30f));
;               }
;             asm volatile("" ::: "memory");
;           }
	v_pk_mul_f32 v[144:145], v[144:145], s[16:17] op_sel_hi:[1,0]
	v_pk_mul_f32 v[146:147], v[146:147], s[16:17] op_sel_hi:[1,0]
	v_pk_mul_f32 v[140:141], v[140:141], s[16:17] op_sel_hi:[1,0]
	v_pk_mul_f32 v[142:143], v[142:143], s[16:17] op_sel_hi:[1,0]
	v_max_f32_e32 v144, 0xda24260, v144
	v_max_f32_e32 v145, 0xda24260, v145
	v_max_f32_e32 v146, 0xda24260, v146
	v_max_f32_e32 v147, 0xda24260, v147
	v_rcp_f32_e32 v144, v144
	v_rcp_f32_e32 v145, v145
	v_rcp_f32_e32 v146, v146
	v_rcp_f32_e32 v147, v147
	v_pk_mul_f32 v[140:141], v[140:141], v[144:145]
	v_pk_mul_f32 v[142:143], v[142:143], v[146:147]
	v_pk_mul_f32 v[116:117], v[116:117], v[140:141]
	v_pk_mul_f32 v[118:119], v[118:119], v[142:143]
	v_cvt_f32_ubyte0_e32 v144, v174
	v_cvt_f32_ubyte1_e32 v145, v174
	v_cvt_f32_ubyte2_e32 v146, v174
	v_cvt_f32_ubyte3_e32 v147, v174
	v_cvt_f32_ubyte0_e32 v140, v170
	v_cvt_f32_ubyte1_e32 v141, v170
	v_cvt_f32_ubyte2_e32 v142, v170
	v_cvt_f32_ubyte3_e32 v143, v170
	v_pk_mul_f32 v[144:145], v[144:145], s[16:17] op_sel_hi:[1,0]
	v_pk_mul_f32 v[146:147], v[146:147], s[16:17] op_sel_hi:[1,0]
	v_pk_mul_f32 v[140:141], v[140:141], s[16:17] op_sel_hi:[1,0]
	v_pk_mul_f32 v[142:143], v[142:143], s[16:17] op_sel_hi:[1,0]
	v_max_f32_e32 v144, 0xda24260, v144
	v_max_f32_e32 v145, 0xda24260, v145
	v_max_f32_e32 v146, 0xda24260, v146
	v_max_f32_e32 v147, 0xda24260, v147
	v_rcp_f32_e32 v144, v144
	v_rcp_f32_e32 v145, v145
	v_rcp_f32_e32 v146, v146
	v_rcp_f32_e32 v147, v147
	v_pk_mul_f32 v[140:141], v[140:141], v[144:145]
	v_pk_mul_f32 v[142:143], v[142:143], v[146:147]
	v_pk_mul_f32 v[108:109], v[108:109], v[140:141]
	v_pk_mul_f32 v[110:111], v[110:111], v[142:143]
	v_cvt_f32_ubyte0_e32 v144, v175
	v_cvt_f32_ubyte1_e32 v145, v175
	v_cvt_f32_ubyte2_e32 v146, v175
	v_cvt_f32_ubyte3_e32 v147, v175
	v_cvt_f32_ubyte0_e32 v140, v171
	v_cvt_f32_ubyte1_e32 v141, v171
	v_cvt_f32_ubyte2_e32 v142, v171
	v_cvt_f32_ubyte3_e32 v143, v171
	v_pk_mul_f32 v[144:145], v[144:145], s[16:17] op_sel_hi:[1,0]
	v_pk_mul_f32 v[146:147], v[146:147], s[16:17] op_sel_hi:[1,0]
	v_pk_mul_f32 v[140:141], v[140:141], s[16:17] op_sel_hi:[1,0]
	v_pk_mul_f32 v[142:143], v[142:143], s[16:17] op_sel_hi:[1,0]
	v_max_f32_e32 v144, 0xda24260, v144
	v_max_f32_e32 v145, 0xda24260, v145
	v_max_f32_e32 v146, 0xda24260, v146
	v_max_f32_e32 v147, 0xda24260, v147
	v_rcp_f32_e32 v144, v144
	v_rcp_f32_e32 v145, v145
	v_rcp_f32_e32 v146, v146
	v_rcp_f32_e32 v147, v147
	v_pk_mul_f32 v[140:141], v[140:141], v[144:145]
	v_pk_mul_f32 v[142:143], v[142:143], v[146:147]
	v_pk_mul_f32 v[100:101], v[100:101], v[140:141]
	v_pk_mul_f32 v[102:103], v[102:103], v[142:143]
	s_waitcnt vmcnt(8)
	v_permlane16_swap_b32 v176, v177
	v_permlane16_swap_b32 v178, v179
	v_permlane16_swap_b32 v180, v181
	v_permlane16_swap_b32 v182, v183
	v_permlane32_swap_b32 v176, v178
	v_permlane32_swap_b32 v177, v179
	v_permlane32_swap_b32 v180, v182
	v_permlane32_swap_b32 v181, v183
	v_cvt_f32_ubyte0_e32 v144, v180
	v_cvt_f32_ubyte1_e32 v145, v180
	v_cvt_f32_ubyte2_e32 v146, v180
	v_cvt_f32_ubyte3_e32 v147, v180
	v_cvt_f32_ubyte0_e32 v140, v176
	v_cvt_f32_ubyte1_e32 v141, v176
	v_cvt_f32_ubyte2_e32 v142, v176
	v_cvt_f32_ubyte3_e32 v143, v176
	v_pk_mul_f32 v[144:145], v[144:145], s[16:17] op_sel_hi:[1,0]
	v_pk_mul_f32 v[146:147], v[146:147], s[16:17] op_sel_hi:[1,0]
	v_pk_mul_f32 v[140:141], v[140:141], s[16:17] op_sel_hi:[1,0]
	v_pk_mul_f32 v[142:143], v[142:143], s[16:17] op_sel_hi:[1,0]
	v_max_f32_e32 v144, 0xda24260, v144
	v_max_f32_e32 v145, 0xda24260, v145
	v_max_f32_e32 v146, 0xda24260, v146
	v_max_f32_e32 v147, 0xda24260, v147
	v_rcp_f32_e32 v144, v144
	v_rcp_f32_e32 v145, v145
	v_rcp_f32_e32 v146, v146
	v_rcp_f32_e32 v147, v147
	v_pk_mul_f32 v[140:141], v[140:141], v[144:145]
	v_pk_mul_f32 v[142:143], v[142:143], v[146:147]
	v_pk_mul_f32 v[60:61], v[60:61], v[140:141]
	v_pk_mul_f32 v[62:63], v[62:63], v[142:143]
	v_cvt_f32_ubyte0_e32 v144, v181
	v_cvt_f32_ubyte1_e32 v145, v181
	v_cvt_f32_ubyte2_e32 v146, v181
	v_cvt_f32_ubyte3_e32 v147, v181
	v_cvt_f32_ubyte0_e32 v140, v177
	v_cvt_f32_ubyte1_e32 v141, v177
	v_cvt_f32_ubyte2_e32 v142, v177
	v_cvt_f32_ubyte3_e32 v143, v177
	v_pk_mul_f32 v[144:145], v[144:145], s[16:17] op_sel_hi:[1,0]
	v_pk_mul_f32 v[146:147], v[146:147], s[16:17] op_sel_hi:[1,0]
	v_pk_mul_f32 v[140:141], v[140:141], s[16:17] op_sel_hi:[1,0]
	v_pk_mul_f32 v[142:143], v[142:143], s[16:17] op_sel_hi:[1,0]
	v_max_f32_e32 v144, 0xda24260, v144
	v_max_f32_e32 v145, 0xda24260, v145
	v_max_f32_e32 v146, 0xda24260, v146
	v_max_f32_e32 v147, 0xda24260, v147
	v_rcp_f32_e32 v144, v144
	v_rcp_f32_e32 v145, v145
	v_rcp_f32_e32 v146, v146
	v_rcp_f32_e32 v147, v147
	v_pk_mul_f32 v[140:141], v[140:141], v[144:145]
	v_pk_mul_f32 v[142:143], v[142:143], v[146:147]
	v_pk_mul_f32 v[52:53], v[52:53], v[140:141]
	v_pk_mul_f32 v[54:55], v[54:55], v[142:143]
	v_cvt_f32_ubyte0_e32 v144, v182
	v_cvt_f32_ubyte1_e32 v145, v182
	v_cvt_f32_ubyte2_e32 v146, v182
	v_cvt_f32_ubyte3_e32 v147, v182
	v_cvt_f32_ubyte0_e32 v140, v178
	v_cvt_f32_ubyte1_e32 v141, v178
	v_cvt_f32_ubyte2_e32 v142, v178
	v_cvt_f32_ubyte3_e32 v143, v178
	v_pk_mul_f32 v[144:145], v[144:145], s[16:17] op_sel_hi:[1,0]
	v_pk_mul_f32 v[146:147], v[146:147], s[16:17] op_sel_hi:[1,0]
	v_pk_mul_f32 v[140:141], v[140:141], s[16:17] op_sel_hi:[1,0]
	v_pk_mul_f32 v[142:143], v[142:143], s[16:17] op_sel_hi:[1,0]
	v_max_f32_e32 v144, 0xda24260, v144
	v_max_f32_e32 v145, 0xda24260, v145
	v_max_f32_e32 v146, 0xda24260, v146
	v_max_f32_e32 v147, 0xda24260, v147
	v_rcp_f32_e32 v144, v144
	v_rcp_f32_e32 v145, v145
	v_rcp_f32_e32 v146, v146
	v_rcp_f32_e32 v147, v147
	v_pk_mul_f32 v[140:141], v[140:141], v[144:145]
	v_pk_mul_f32 v[142:143], v[142:143], v[146:147]
	v_pk_mul_f32 v[44:45], v[44:45], v[140:141]
	v_pk_mul_f32 v[46:47], v[46:47], v[142:143]
	v_cvt_f32_ubyte0_e32 v144, v183
	v_cvt_f32_ubyte1_e32 v145, v183
	v_cvt_f32_ubyte2_e32 v146, v183
	v_cvt_f32_ubyte3_e32 v147, v183
	v_cvt_f32_ubyte0_e32 v140, v179
	v_cvt_f32_ubyte1_e32 v141, v179
	v_cvt_f32_ubyte2_e32 v142, v179
	v_cvt_f32_ubyte3_e32 v143, v179
	v_pk_mul_f32 v[144:145], v[144:145], s[16:17] op_sel_hi:[1,0]
	v_pk_mul_f32 v[146:147], v[146:147], s[16:17] op_sel_hi:[1,0]
	v_pk_mul_f32 v[140:141], v[140:141], s[16:17] op_sel_hi:[1,0]
	v_pk_mul_f32 v[142:143], v[142:143], s[16:17] op_sel_hi:[1,0]
	v_max_f32_e32 v144, 0xda24260, v144
	v_max_f32_e32 v145, 0xda24260, v145
	v_max_f32_e32 v146, 0xda24260, v146
	v_max_f32_e32 v147, 0xda24260, v147
	v_rcp_f32_e32 v144, v144
	v_rcp_f32_e32 v145, v145
	v_rcp_f32_e32 v146, v146
	v_rcp_f32_e32 v147, v147
	v_pk_mul_f32 v[140:141], v[140:141], v[144:145]
	v_pk_mul_f32 v[142:143], v[142:143], v[146:147]
	v_pk_mul_f32 v[36:37], v[36:37], v[140:141]
	v_pk_mul_f32 v[38:39], v[38:39], v[142:143]
	s_waitcnt vmcnt(6)
; __device__ __forceinline__ float u8f(unsigned w, int i) { return (float)((w >> (8 * i)) & 0xffu) * (1.f / 255.f); }
; __device__ void phase4(const Params& p) {
;     ...
;       if (seg == 0) {
;         #pragma unroll
;         for (int bj = 0; bj < 2; ++bj)
;           #pragma unroll
;           for (int n = 0; n < 2; ++n) {
;             const size_t base = (size_t)EPI_T(bj, n) * D + lanef;
;             const unsigned* pa = reinterpret_cast<const unsigned*>(reinterpret_cast<const unsigned char*>(sga) + base);
;             const unsigned* pb = reinterpret_cast<const unsigned*>(reinterpret_cast<const unsigned char*>(sgb) + base);
;             #pragma unroll
;             for (int ai = 0; ai < 2; ++ai)
;               #pragma unroll
;               for (int m = 0; m < 4; ++m) {
;                 const unsigned ga = pa[(ai * 128 + m * 16) / 4];
;                 const unsigned gb = pb[(ai * 128 + m * 16) / 4];
;                 #pragma unroll
;                 for (int j = 0; j < 4; ++j)
;                   acc[ai][bj][m][n][j] *= u8f(ga, j) * __builtin_amdgcn_rcpf(fmaxf(u8f(gb, j), 1e-30f));
;               }
;             asm volatile("" ::: "memory");
;           }
	v_permlane16_swap_b32 v184, v185
	v_permlane16_swap_b32 v186, v187
	v_permlane16_swap_b32 v188, v189
	v_permlane16_swap_b32 v190, v191
	v_permlane32_swap_b32 v184, v186
	v_permlane32_swap_b32 v185, v187
	v_permlane32_swap_b32 v188, v190
	v_permlane32_swap_b32 v189, v191
	v_cvt_f32_ubyte0_e32 v144, v188
	v_cvt_f32_ubyte1_e32 v145, v188
	v_cvt_f32_ubyte2_e32 v146, v188
	v_cvt_f32_ubyte3_e32 v147, v188
	v_cvt_f32_ubyte0_e32 v140, v184
	v_cvt_f32_ubyte1_e32 v141, v184
	v_cvt_f32_ubyte2_e32 v142, v184
	v_cvt_f32_ubyte3_e32 v143, v184
	v_pk_mul_f32 v[144:145], v[144:145], s[16:17] op_sel_hi:[1,0]
	v_pk_mul_f32 v[146:147], v[146:147], s[16:17] op_sel_hi:[1,0]
	v_pk_mul_f32 v[140:141], v[140:141], s[16:17] op_sel_hi:[1,0]
	v_pk_mul_f32 v[142:143], v[142:143], s[16:17] op_sel_hi:[1,0]
	v_max_f32_e32 v144, 0xda24260, v144
	v_max_f32_e32 v145, 0xda24260, v145
	v_max_f32_e32 v146, 0xda24260, v146
	v_max_f32_e32 v147, 0xda24260, v147
	v_rcp_f32_e32 v144, v144
	v_rcp_f32_e32 v145, v145
	v_rcp_f32_e32 v146, v146
	v_rcp_f32_e32 v147, v147
	v_pk_mul_f32 v[140:141], v[140:141], v[144:145]
	v_pk_mul_f32 v[142:143], v[142:143], v[146:147]
	v_pk_mul_f32 v[96:97], v[96:97], v[140:141]
	v_pk_mul_f32 v[98:99], v[98:99], v[142:143]
	v_cvt_f32_ubyte0_e32 v144, v189
	v_cvt_f32_ubyte1_e32 v145, v189
	v_cvt_f32_ubyte2_e32 v146, v189
	v_cvt_f32_ubyte3_e32 v147, v189
	v_cvt_f32_ubyte0_e32 v140, v185
	v_cvt_f32_ubyte1_e32 v141, v185
	v_cvt_f32_ubyte2_e32 v142, v185
	v_cvt_f32_ubyte3_e32 v143, v185
	v_pk_mul_f32 v[144:145], v[144:145], s[16:17] op_sel_hi:[1,0]
	v_pk_mul_f32 v[146:147], v[146:147], s[16:17] op_sel_hi:[1,0]
	v_pk_mul_f32 v[140:141], v[140:141], s[16:17] op_sel_hi:[1,0]
	v_pk_mul_f32 v[142:143], v[142:143], s[16:17] op_sel_hi:[1,0]
	v_max_f32_e32 v144, 0xda24260, v144
	v_max_f32_e32 v145, 0xda24260, v145
	v_max_f32_e32 v146, 0xda24260, v146
	v_max_f32_e32 v147, 0xda24260, v147
	v_rcp_f32_e32 v144, v144
	v_rcp_f32_e32 v145, v145
	v_rcp_f32_e32 v146, v146
	v_rcp_f32_e32 v147, v147
	v_pk_mul_f32 v[140:141], v[140:141], v[144:145]
	v_pk_mul_f32 v[142:143], v[142:143], v[146:147]
	v_pk_mul_f32 v[88:89], v[88:89], v[140:141]
	v_pk_mul_f32 v[90:91], v[90:91], v[142:143]
	v_cvt_f32_ubyte0_e32 v144, v190
	v_cvt_f32_ubyte1_e32 v145, v190
	v_cvt_f32_ubyte2_e32 v146, v190
	v_cvt_f32_ubyte3_e32 v147, v190
	v_cvt_f32_ubyte0_e32 v140, v186
	v_cvt_f32_ubyte1_e32 v141, v186
	v_cvt_f32_ubyte2_e32 v142, v186
	v_cvt_f32_ubyte3_e32 v143, v186
	v_pk_mul_f32 v[144:145], v[144:145], s[16:17] op_sel_hi:[1,0]
	v_pk_mul_f32 v[146:147], v[146:147], s[16:17] op_sel_hi:[1,0]
	v_pk_mul_f32 v[140:141], v[140:141], s[16:17] op_sel_hi:[1,0]
	v_pk_mul_f32 v[142:143], v[142:143], s[16:17] op_sel_hi:[1,0]
	v_max_f32_e32 v144, 0xda24260, v144
	v_max_f32_e32 v145, 0xda24260, v145
	v_max_f32_e32 v146, 0xda24260, v146
	v_max_f32_e32 v147, 0xda24260, v147
	v_rcp_f32_e32 v144, v144
	v_rcp_f32_e32 v145, v145
	v_rcp_f32_e32 v146, v146
	v_rcp_f32_e32 v147, v147
	v_pk_mul_f32 v[140:141], v[140:141], v[144:145]
	v_pk_mul_f32 v[142:143], v[142:143], v[146:147]
	v_pk_mul_f32 v[80:81], v[80:81], v[140:141]
	v_pk_mul_f32 v[82:83], v[82:83], v[142:143]
	v_cvt_f32_ubyte0_e32 v144, v191
	v_cvt_f32_ubyte1_e32 v145, v191
	v_cvt_f32_ubyte2_e32 v146, v191
	v_cvt_f32_ubyte3_e32 v147, v191
	v_cvt_f32_ubyte0_e32 v140, v187
	v_cvt_f32_ubyte1_e32 v141, v187
	v_cvt_f32_ubyte2_e32 v142, v187
	v_cvt_f32_ubyte3_e32 v143, v187
	v_pk_mul_f32 v[144:145], v[144:145], s[16:17] op_sel_hi:[1,0]
	v_pk_mul_f32 v[146:147], v[146:147], s[16:17] op_sel_hi:[1,0]
	v_pk_mul_f32 v[140:141], v[140:141], s[16:17] op_sel_hi:[1,0]
	v_pk_mul_f32 v[142:143], v[142:143], s[16:17] op_sel_hi:[1,0]
	v_max_f32_e32 v144, 0xda24260, v144
	v_max_f32_e32 v145, 0xda24260, v145
	v_max_f32_e32 v146, 0xda24260, v146
	v_max_f32_e32 v147, 0xda24260, v147
	v_rcp_f32_e32 v144, v144
	v_rcp_f32_e32 v145, v145
	v_rcp_f32_e32 v146, v146
	v_rcp_f32_e32 v147, v147
	v_pk_mul_f32 v[140:141], v[140:141], v[144:145]
	v_pk_mul_f32 v[142:143], v[142:143], v[146:147]
	v_pk_mul_f32 v[72:73], v[72:73], v[140:141]
	v_pk_mul_f32 v[74:75], v[74:75], v[142:143]
	s_waitcnt vmcnt(4)
	v_permlane16_swap_b32 v196, v197
	v_permlane16_swap_b32 v198, v199
	v_permlane16_swap_b32 v200, v201
	v_permlane16_swap_b32 v202, v203
	v_permlane32_swap_b32 v196, v198
	v_permlane32_swap_b32 v197, v199
	v_permlane32_swap_b32 v200, v202
	v_permlane32_swap_b32 v201, v203
	v_cvt_f32_ubyte0_e32 v144, v200
	v_cvt_f32_ubyte1_e32 v145, v200
	v_cvt_f32_ubyte2_e32 v146, v200
	v_cvt_f32_ubyte3_e32 v147, v200
	v_cvt_f32_ubyte0_e32 v140, v196
	v_cvt_f32_ubyte1_e32 v141, v196
	v_cvt_f32_ubyte2_e32 v142, v196
	v_cvt_f32_ubyte3_e32 v143, v196
	v_pk_mul_f32 v[144:145], v[144:145], s[16:17] op_sel_hi:[1,0]
	v_pk_mul_f32 v[146:147], v[146:147], s[16:17] op_sel_hi:[1,0]
	v_pk_mul_f32 v[140:141], v[140:141], s[16:17] op_sel_hi:[1,0]
	v_pk_mul_f32 v[142:143], v[142:143], s[16:17] op_sel_hi:[1,0]
	v_max_f32_e32 v144, 0xda24260, v144
	v_max_f32_e32 v145, 0xda24260, v145
	v_max_f32_e32 v146, 0xda24260, v146
	v_max_f32_e32 v147, 0xda24260, v147
	v_rcp_f32_e32 v144, v144
	v_rcp_f32_e32 v145, v145
	v_rcp_f32_e32 v146, v146
	v_rcp_f32_e32 v147, v147
	v_pk_mul_f32 v[140:141], v[140:141], v[144:145]
	v_pk_mul_f32 v[142:143], v[142:143], v[146:147]
	v_pk_mul_f32 v[32:33], v[32:33], v[140:141]
	v_pk_mul_f32 v[34:35], v[34:35], v[142:143]
	v_cvt_f32_ubyte0_e32 v144, v201
	v_cvt_f32_ubyte1_e32 v145, v201
	v_cvt_f32_ubyte2_e32 v146, v201
	v_cvt_f32_ubyte3_e32 v147, v201
	v_cvt_f32_ubyte0_e32 v140, v197
	v_cvt_f32_ubyte1_e32 v141, v197
	v_cvt_f32_ubyte2_e32 v142, v197
	v_cvt_f32_ubyte3_e32 v143, v197
	v_pk_mul_f32 v[144:145], v[144:145], s[16:17] op_sel_hi:[1,0]
; __device__ __forceinline__ float u8f(unsigned w, int i) { return (float)((w >> (8 * i)) & 0xffu) * (1.f / 255.f); }
; __device__ void phase4(const Params& p) {
;     ...
;       if (seg == 0) {
;         #pragma unroll
;         for (int bj = 0; bj < 2; ++bj)
;           #pragma unroll
;           for (int n = 0; n < 2; ++n) {
;             const size_t base = (size_t)EPI_T(bj, n) * D + lanef;
;             const unsigned* pa = reinterpret_cast<const unsigned*>(reinterpret_cast<const unsigned char*>(sga) + base);
;             const unsigned* pb = reinterpret_cast<const unsigned*>(reinterpret_cast<const unsigned char*>(sgb) + base);
;             #pragma unroll
;             for (int ai = 0; ai < 2; ++ai)
;               #pragma unroll
;               for (int m = 0; m < 4; ++m) {
;                 const unsigned ga = pa[(ai * 128 + m * 16) / 4];
;                 const unsigned gb = pb[(ai * 128 + m * 16) / 4];
;                 #pragma unroll
;                 for (int j = 0; j < 4; ++j)
;                   acc[ai][bj][m][n][j] *= u8f(ga, j) * __builtin_amdgcn_rcpf(fmaxf(u8f(gb, j), 1e-30f));
;               }
;             asm volatile("" ::: "memory");
;           }
	v_pk_mul_f32 v[146:147], v[146:147], s[16:17] op_sel_hi:[1,0]
	v_pk_mul_f32 v[140:141], v[140:141], s[16:17] op_sel_hi:[1,0]
	v_pk_mul_f32 v[142:143], v[142:143], s[16:17] op_sel_hi:[1,0]
	v_max_f32_e32 v144, 0xda24260, v144
	v_max_f32_e32 v145, 0xda24260, v145
	v_max_f32_e32 v146, 0xda24260, v146
	v_max_f32_e32 v147, 0xda24260, v147
	v_rcp_f32_e32 v144, v144
	v_rcp_f32_e32 v145, v145
	v_rcp_f32_e32 v146, v146
	v_rcp_f32_e32 v147, v147
	v_pk_mul_f32 v[140:141], v[140:141], v[144:145]
	v_pk_mul_f32 v[142:143], v[142:143], v[146:147]
	v_pk_mul_f32 v[24:25], v[24:25], v[140:141]
	v_pk_mul_f32 v[26:27], v[26:27], v[142:143]
	v_cvt_f32_ubyte0_e32 v144, v202
	v_cvt_f32_ubyte1_e32 v145, v202
	v_cvt_f32_ubyte2_e32 v146, v202
	v_cvt_f32_ubyte3_e32 v147, v202
	v_cvt_f32_ubyte0_e32 v140, v198
	v_cvt_f32_ubyte1_e32 v141, v198
	v_cvt_f32_ubyte2_e32 v142, v198
	v_cvt_f32_ubyte3_e32 v143, v198
	v_pk_mul_f32 v[144:145], v[144:145], s[16:17] op_sel_hi:[1,0]
	v_pk_mul_f32 v[146:147], v[146:147], s[16:17] op_sel_hi:[1,0]
	v_pk_mul_f32 v[140:141], v[140:141], s[16:17] op_sel_hi:[1,0]
	v_pk_mul_f32 v[142:143], v[142:143], s[16:17] op_sel_hi:[1,0]
	v_max_f32_e32 v144, 0xda24260, v144
	v_max_f32_e32 v145, 0xda24260, v145
	v_max_f32_e32 v146, 0xda24260, v146
	v_max_f32_e32 v147, 0xda24260, v147
	v_rcp_f32_e32 v144, v144
	v_rcp_f32_e32 v145, v145
	v_rcp_f32_e32 v146, v146
	v_rcp_f32_e32 v147, v147
	v_pk_mul_f32 v[140:141], v[140:141], v[144:145]
	v_pk_mul_f32 v[142:143], v[142:143], v[146:147]
	v_pk_mul_f32 v[16:17], v[16:17], v[140:141]
	v_pk_mul_f32 v[18:19], v[18:19], v[142:143]
	v_cvt_f32_ubyte0_e32 v144, v203
	v_cvt_f32_ubyte1_e32 v145, v203
	v_cvt_f32_ubyte2_e32 v146, v203
	v_cvt_f32_ubyte3_e32 v147, v203
	v_cvt_f32_ubyte0_e32 v140, v199
	v_cvt_f32_ubyte1_e32 v141, v199
	v_cvt_f32_ubyte2_e32 v142, v199
	v_cvt_f32_ubyte3_e32 v143, v199
	v_pk_mul_f32 v[144:145], v[144:145], s[16:17] op_sel_hi:[1,0]
	v_pk_mul_f32 v[146:147], v[146:147], s[16:17] op_sel_hi:[1,0]
	v_pk_mul_f32 v[140:141], v[140:141], s[16:17] op_sel_hi:[1,0]
	v_pk_mul_f32 v[142:143], v[142:143], s[16:17] op_sel_hi:[1,0]
	v_max_f32_e32 v144, 0xda24260, v144
	v_max_f32_e32 v145, 0xda24260, v145
	v_max_f32_e32 v146, 0xda24260, v146
	v_max_f32_e32 v147, 0xda24260, v147
	v_rcp_f32_e32 v144, v144
	v_rcp_f32_e32 v145, v145
	v_rcp_f32_e32 v146, v146
	v_rcp_f32_e32 v147, v147
	v_pk_mul_f32 v[140:141], v[140:141], v[144:145]
	v_pk_mul_f32 v[142:143], v[142:143], v[146:147]
	v_pk_mul_f32 v[8:9], v[8:9], v[140:141]
	v_pk_mul_f32 v[10:11], v[10:11], v[142:143]
	s_waitcnt vmcnt(2)
	v_permlane16_swap_b32 v204, v205
	v_permlane16_swap_b32 v206, v207
	v_permlane16_swap_b32 v208, v209
	v_permlane16_swap_b32 v210, v211
	v_permlane32_swap_b32 v204, v206
	v_permlane32_swap_b32 v205, v207
	v_permlane32_swap_b32 v208, v210
	v_permlane32_swap_b32 v209, v211
	v_cvt_f32_ubyte0_e32 v144, v208
	v_cvt_f32_ubyte1_e32 v145, v208
	v_cvt_f32_ubyte2_e32 v146, v208
	v_cvt_f32_ubyte3_e32 v147, v208
	v_cvt_f32_ubyte0_e32 v140, v204
	v_cvt_f32_ubyte1_e32 v141, v204
	v_cvt_f32_ubyte2_e32 v142, v204
	v_cvt_f32_ubyte3_e32 v143, v204
	v_pk_mul_f32 v[144:145], v[144:145], s[16:17] op_sel_hi:[1,0]
	v_pk_mul_f32 v[146:147], v[146:147], s[16:17] op_sel_hi:[1,0]
	v_pk_mul_f32 v[140:141], v[140:141], s[16:17] op_sel_hi:[1,0]
	v_pk_mul_f32 v[142:143], v[142:143], s[16:17] op_sel_hi:[1,0]
	v_max_f32_e32 v144, 0xda24260, v144
	v_max_f32_e32 v145, 0xda24260, v145
	v_max_f32_e32 v146, 0xda24260, v146
	v_max_f32_e32 v147, 0xda24260, v147
	v_rcp_f32_e32 v144, v144
	v_rcp_f32_e32 v145, v145
	v_rcp_f32_e32 v146, v146
	v_rcp_f32_e32 v147, v147
	v_pk_mul_f32 v[140:141], v[140:141], v[144:145]
	v_pk_mul_f32 v[142:143], v[142:143], v[146:147]
	v_pk_mul_f32 v[92:93], v[92:93], v[140:141]
	v_pk_mul_f32 v[94:95], v[94:95], v[142:143]
	v_cvt_f32_ubyte0_e32 v144, v209
	v_cvt_f32_ubyte1_e32 v145, v209
	v_cvt_f32_ubyte2_e32 v146, v209
	v_cvt_f32_ubyte3_e32 v147, v209
	v_cvt_f32_ubyte0_e32 v140, v205
	v_cvt_f32_ubyte1_e32 v141, v205
	v_cvt_f32_ubyte2_e32 v142, v205
	v_cvt_f32_ubyte3_e32 v143, v205
	v_pk_mul_f32 v[144:145], v[144:145], s[16:17] op_sel_hi:[1,0]
	v_pk_mul_f32 v[146:147], v[146:147], s[16:17] op_sel_hi:[1,0]
	v_pk_mul_f32 v[140:141], v[140:141], s[16:17] op_sel_hi:[1,0]
	v_pk_mul_f32 v[142:143], v[142:143], s[16:17] op_sel_hi:[1,0]
	v_max_f32_e32 v144, 0xda24260, v144
	v_max_f32_e32 v145, 0xda24260, v145
	v_max_f32_e32 v146, 0xda24260, v146
	v_max_f32_e32 v147, 0xda24260, v147
	v_rcp_f32_e32 v144, v144
	v_rcp_f32_e32 v145, v145
	v_rcp_f32_e32 v146, v146
	v_rcp_f32_e32 v147, v147
	v_pk_mul_f32 v[140:141], v[140:141], v[144:145]
	v_pk_mul_f32 v[142:143], v[142:143], v[146:147]
	v_pk_mul_f32 v[84:85], v[84:85], v[140:141]
	v_pk_mul_f32 v[86:87], v[86:87], v[142:143]
	v_cvt_f32_ubyte0_e32 v144, v210
	v_cvt_f32_ubyte1_e32 v145, v210
	v_cvt_f32_ubyte2_e32 v146, v210
	v_cvt_f32_ubyte3_e32 v147, v210
	v_cvt_f32_ubyte0_e32 v140, v206
	v_cvt_f32_ubyte1_e32 v141, v206
	v_cvt_f32_ubyte2_e32 v142, v206
	v_cvt_f32_ubyte3_e32 v143, v206
	v_pk_mul_f32 v[144:145], v[144:145], s[16:17] op_sel_hi:[1,0]
	v_pk_mul_f32 v[146:147], v[146:147], s[16:17] op_sel_hi:[1,0]
	v_pk_mul_f32 v[140:141], v[140:141], s[16:17] op_sel_hi:[1,0]
	v_pk_mul_f32 v[142:143], v[142:143], s[16:17] op_sel_hi:[1,0]
	v_max_f32_e32 v144, 0xda24260, v144
	v_max_f32_e32 v145, 0xda24260, v145
	v_max_f32_e32 v146, 0xda24260, v146
	v_max_f32_e32 v147, 0xda24260, v147
	v_rcp_f32_e32 v144, v144
	v_rcp_f32_e32 v145, v145
	v_rcp_f32_e32 v146, v146
	v_rcp_f32_e32 v147, v147
	v_pk_mul_f32 v[140:141], v[140:141], v[144:145]
	v_pk_mul_f32 v[142:143], v[142:143], v[146:147]
	v_pk_mul_f32 v[76:77], v[76:77], v[140:141]
	v_pk_mul_f32 v[78:79], v[78:79], v[142:143]
	v_cvt_f32_ubyte0_e32 v144, v211
	v_cvt_f32_ubyte1_e32 v145, v211
	v_cvt_f32_ubyte2_e32 v146, v211
	v_cvt_f32_ubyte3_e32 v147, v211
	v_cvt_f32_ubyte0_e32 v140, v207
	v_cvt_f32_ubyte1_e32 v141, v207
	v_cvt_f32_ubyte2_e32 v142, v207
	v_cvt_f32_ubyte3_e32 v143, v207
	v_pk_mul_f32 v[144:145], v[144:145], s[16:17] op_sel_hi:[1,0]
	v_pk_mul_f32 v[146:147], v[146:147], s[16:17] op_sel_hi:[1,0]
	v_pk_mul_f32 v[140:141], v[140:141], s[16:17] op_sel_hi:[1,0]
	v_pk_mul_f32 v[142:143], v[142:143], s[16:17] op_sel_hi:[1,0]
	v_max_f32_e32 v144, 0xda24260, v144
	v_max_f32_e32 v145, 0xda24260, v145
	v_max_f32_e32 v146, 0xda24260, v146
	v_max_f32_e32 v147, 0xda24260, v147
	v_rcp_f32_e32 v144, v144
	v_rcp_f32_e32 v145, v145
	v_rcp_f32_e32 v146, v146
	v_rcp_f32_e32 v147, v147
	v_pk_mul_f32 v[140:141], v[140:141], v[144:145]
	v_pk_mul_f32 v[142:143], v[142:143], v[146:147]
	v_pk_mul_f32 v[68:69], v[68:69], v[140:141]
	v_pk_mul_f32 v[70:71], v[70:71], v[142:143]
	s_waitcnt vmcnt(0)
; __device__ __forceinline__ float u8f(unsigned w, int i) { return (float)((w >> (8 * i)) & 0xffu) * (1.f / 255.f); }
; __device__ __forceinline__ bool tile_coords(int it, int nM, int nN, int& pm, int& pn) {
;   const int G = gridDim.x, b = blockIdx.x, ntiles = nM * nN;
;   int L;
;   if ((G & 7) == 0 && (it + 1) * G <= ntiles) L = it * G + (b & 7) * (G >> 3) + (b >> 3);
;   else L = it * G + b;
;   if (L >= ntiles) return false;
;   const int nig = 8 * nN, gid = L / nig, fm = gid * 8, gsz = min(nM - fm, 8);
;   pm = fm + (L % nig) % gsz;
;   pn = (L % nig) / gsz;
;   return true;
; __device__ void phase4(const Params& p) {
;     ...
;       if (seg == 0) {
;         #pragma unroll
;         for (int bj = 0; bj < 2; ++bj)
;           #pragma unroll
;           for (int n = 0; n < 2; ++n) {
;             const size_t base = (size_t)EPI_T(bj, n) * D + lanef;
;             const unsigned* pa = reinterpret_cast<const unsigned*>(reinterpret_cast<const unsigned char*>(sga) + base);
;             const unsigned* pb = reinterpret_cast<const unsigned*>(reinterpret_cast<const unsigned char*>(sgb) + base);
;             #pragma unroll
;             for (int ai = 0; ai < 2; ++ai)
;               #pragma unroll
;               for (int m = 0; m < 4; ++m) {
;                 const unsigned ga = pa[(ai * 128 + m * 16) / 4];
;                 const unsigned gb = pb[(ai * 128 + m * 16) / 4];
;                 #pragma unroll
;                 for (int j = 0; j < 4; ++j)
;                   acc[ai][bj][m][n][j] *= u8f(ga, j) * __builtin_amdgcn_rcpf(fmaxf(u8f(gb, j), 1e-30f));
;               }
;             asm volatile("" ::: "memory");
;           }
	v_permlane16_swap_b32 v212, v213
	v_permlane16_swap_b32 v214, v215
	v_permlane16_swap_b32 v216, v217
	v_permlane16_swap_b32 v218, v219
	v_permlane32_swap_b32 v212, v214
	v_permlane32_swap_b32 v213, v215
	v_permlane32_swap_b32 v216, v218
	v_permlane32_swap_b32 v217, v219
	v_cvt_f32_ubyte0_e32 v144, v216
	v_cvt_f32_ubyte1_e32 v145, v216
	v_cvt_f32_ubyte2_e32 v146, v216
	v_cvt_f32_ubyte3_e32 v147, v216
	v_cvt_f32_ubyte0_e32 v140, v212
	v_cvt_f32_ubyte1_e32 v141, v212
	v_cvt_f32_ubyte2_e32 v142, v212
	v_cvt_f32_ubyte3_e32 v143, v212
	v_pk_mul_f32 v[144:145], v[144:145], s[16:17] op_sel_hi:[1,0]
	v_pk_mul_f32 v[146:147], v[146:147], s[16:17] op_sel_hi:[1,0]
	v_pk_mul_f32 v[140:141], v[140:141], s[16:17] op_sel_hi:[1,0]
	v_pk_mul_f32 v[142:143], v[142:143], s[16:17] op_sel_hi:[1,0]
	v_max_f32_e32 v144, 0xda24260, v144
	v_max_f32_e32 v145, 0xda24260, v145
	v_max_f32_e32 v146, 0xda24260, v146
	v_max_f32_e32 v147, 0xda24260, v147
	v_rcp_f32_e32 v144, v144
	v_rcp_f32_e32 v145, v145
	v_rcp_f32_e32 v146, v146
	v_rcp_f32_e32 v147, v147
	v_pk_mul_f32 v[140:141], v[140:141], v[144:145]
	v_pk_mul_f32 v[142:143], v[142:143], v[146:147]
	v_pk_mul_f32 v[28:29], v[28:29], v[140:141]
	v_pk_mul_f32 v[30:31], v[30:31], v[142:143]
	v_cvt_f32_ubyte0_e32 v144, v217
	v_cvt_f32_ubyte1_e32 v145, v217
	v_cvt_f32_ubyte2_e32 v146, v217
	v_cvt_f32_ubyte3_e32 v147, v217
	v_cvt_f32_ubyte0_e32 v140, v213
	v_cvt_f32_ubyte1_e32 v141, v213
	v_cvt_f32_ubyte2_e32 v142, v213
	v_cvt_f32_ubyte3_e32 v143, v213
	v_pk_mul_f32 v[144:145], v[144:145], s[16:17] op_sel_hi:[1,0]
	v_pk_mul_f32 v[146:147], v[146:147], s[16:17] op_sel_hi:[1,0]
	v_pk_mul_f32 v[140:141], v[140:141], s[16:17] op_sel_hi:[1,0]
	v_pk_mul_f32 v[142:143], v[142:143], s[16:17] op_sel_hi:[1,0]
	v_max_f32_e32 v144, 0xda24260, v144
	v_max_f32_e32 v145, 0xda24260, v145
	v_max_f32_e32 v146, 0xda24260, v146
	v_max_f32_e32 v147, 0xda24260, v147
	v_rcp_f32_e32 v144, v144
	v_rcp_f32_e32 v145, v145
	v_rcp_f32_e32 v146, v146
	v_rcp_f32_e32 v147, v147
	v_pk_mul_f32 v[140:141], v[140:141], v[144:145]
	v_pk_mul_f32 v[142:143], v[142:143], v[146:147]
	v_pk_mul_f32 v[20:21], v[20:21], v[140:141]
	v_pk_mul_f32 v[22:23], v[22:23], v[142:143]
	v_cvt_f32_ubyte0_e32 v144, v218
	v_cvt_f32_ubyte1_e32 v145, v218
	v_cvt_f32_ubyte2_e32 v146, v218
	v_cvt_f32_ubyte3_e32 v147, v218
	v_cvt_f32_ubyte0_e32 v140, v214
	v_cvt_f32_ubyte1_e32 v141, v214
	v_cvt_f32_ubyte2_e32 v142, v214
	v_cvt_f32_ubyte3_e32 v143, v214
	v_pk_mul_f32 v[144:145], v[144:145], s[16:17] op_sel_hi:[1,0]
	v_pk_mul_f32 v[146:147], v[146:147], s[16:17] op_sel_hi:[1,0]
	v_pk_mul_f32 v[140:141], v[140:141], s[16:17] op_sel_hi:[1,0]
	v_pk_mul_f32 v[142:143], v[142:143], s[16:17] op_sel_hi:[1,0]
	v_max_f32_e32 v144, 0xda24260, v144
	v_max_f32_e32 v145, 0xda24260, v145
	v_max_f32_e32 v146, 0xda24260, v146
	v_max_f32_e32 v147, 0xda24260, v147
	v_rcp_f32_e32 v144, v144
	v_rcp_f32_e32 v145, v145
	v_rcp_f32_e32 v146, v146
	v_rcp_f32_e32 v147, v147
	v_pk_mul_f32 v[140:141], v[140:141], v[144:145]
	v_pk_mul_f32 v[142:143], v[142:143], v[146:147]
	v_pk_mul_f32 v[12:13], v[12:13], v[140:141]
	v_pk_mul_f32 v[14:15], v[14:15], v[142:143]
	v_cvt_f32_ubyte0_e32 v144, v219
	v_cvt_f32_ubyte1_e32 v145, v219
	v_cvt_f32_ubyte2_e32 v146, v219
	v_cvt_f32_ubyte3_e32 v147, v219
	v_cvt_f32_ubyte0_e32 v140, v215
	v_cvt_f32_ubyte1_e32 v141, v215
	v_cvt_f32_ubyte2_e32 v142, v215
	v_cvt_f32_ubyte3_e32 v143, v215
	v_pk_mul_f32 v[144:145], v[144:145], s[16:17] op_sel_hi:[1,0]
	v_pk_mul_f32 v[146:147], v[146:147], s[16:17] op_sel_hi:[1,0]
	v_pk_mul_f32 v[140:141], v[140:141], s[16:17] op_sel_hi:[1,0]
	v_pk_mul_f32 v[142:143], v[142:143], s[16:17] op_sel_hi:[1,0]
	v_max_f32_e32 v144, 0xda24260, v144
	v_max_f32_e32 v145, 0xda24260, v145
	v_max_f32_e32 v146, 0xda24260, v146
	v_max_f32_e32 v147, 0xda24260, v147
	v_rcp_f32_e32 v144, v144
	v_rcp_f32_e32 v145, v145
	v_rcp_f32_e32 v146, v146
	v_rcp_f32_e32 v147, v147
	v_pk_mul_f32 v[140:141], v[140:141], v[144:145]
	v_pk_mul_f32 v[142:143], v[142:143], v[146:147]
	v_pk_mul_f32 v[4:5], v[4:5], v[140:141]
	v_pk_mul_f32 v[6:7], v[6:7], v[142:143]
	s_branch .LBB0_599
.Lp4e_seg1:
	s_add_i32 s24, s77, 1
	s_mul_i32 s25, s24, s33
	s_add_i32 s54, s25, s33
	s_mov_b32 s55, s2
	s_and_b32 s56, s33, 7
	s_cmp_lg_u32 s56, 0
	s_cbranch_scc1 .Lp4n_base
	s_cmpk_gt_i32 s54, 0x500
	s_cbranch_scc1 .Lp4n_base
	s_mov_b32 s55, s35
.Lp4n_base:
	s_add_i32 s24, s55, s25
	s_mov_b32 s100, 0
	s_cmpk_gt_i32 s24, 0x4ff
	s_cbranch_scc1 .Lp4n_done
	s_lshr_b32 s25, s24, 6
	s_and_b32 s54, s24, 7
	s_lshl_b32 s25, s25, 3
	s_add_i32 s25, s25, s54
	s_lshl_b32 s25, s25, 8
	s_bfe_u32 s54, s24, 0x30003
	s_lshl_b32 s54, s54, 8
	v_lshrrev_b32_e32 v248, 1, v246
	v_lshrrev_b32_e32 v250, 10, v248
	v_and_b32_e32 v248, 0x3ff, v248
	v_lshl_add_u32 v248, v250, 11, v248
	v_lshlrev_b32_e32 v250, 1, v248
	v_lshrrev_b32_e32 v249, 1, v247
	v_lshrrev_b32_e32 v251, 10, v249
	v_and_b32_e32 v249, 0x3ff, v249
	v_lshl_add_u32 v249, v251, 11, v249
	v_lshlrev_b32_e32 v251, 1, v249
	s_lshl_b32 s55, s25, 12
	s_add_u32 s58, s28, s55
	s_addc_u32 s59, s29, 0
	s_or_b32 s55, s25, 0x80
	s_lshl_b32 s55, s55, 12
	s_add_u32 s60, s28, s55
	s_addc_u32 s61, s29, 0
	s_lshl_b32 s55, s54, 12
	s_add_u32 s55, s55, 0x2900000
	s_add_u32 s62, s30, s55
	s_addc_u32 s63, s31, 0
	s_or_b32 s55, s54, 0x80
	s_lshl_b32 s55, s55, 12
	s_add_u32 s55, s55, 0x2900000
	s_add_u32 s64, s30, s55
	s_addc_u32 s65, s31, 0
	v_lshrrev_b32_e32 v252, 6, v194
	s_nop 0
	v_readfirstlane_b32 s66, v252
	s_lshl_b32 s66, s66, 10
	s_add_u32 m0, s66, 0x10000
	s_nop 0
	global_load_lds_dwordx4 v250, s[58:59]
	s_add_u32 m0, s66, 0x12000
	s_nop 0
	global_load_lds_dwordx4 v251, s[58:59]
	s_add_u32 m0, s66, 0x0
	s_nop 0
	global_load_lds_dwordx4 v250, s[62:63]
	s_add_u32 m0, s66, 0x2000
	s_nop 0
	global_load_lds_dwordx4 v251, s[62:63]
	s_add_u32 m0, s66, 0x14000
	s_nop 0
	global_load_lds_dwordx4 v250, s[60:61]
	s_add_u32 m0, s66, 0x16000
	s_nop 0
	global_load_lds_dwordx4 v251, s[60:61]
	s_add_u32 m0, s66, 0x4000
	s_nop 0
	global_load_lds_dwordx4 v250, s[64:65]
	s_add_u32 m0, s66, 0x6000
	s_nop 0
	global_load_lds_dwordx4 v251, s[64:65]
	s_mov_b32 s100, 1

; #define WAIT_L(n) asm volatile("s_waitcnt lgkmcnt(" #n ")" ::: "memory")
; #define BAR __builtin_amdgcn_s_barrier()
; __device__ __forceinline__ float sigm(float x) {
;   return __builtin_amdgcn_rcpf(1.f + __builtin_amdgcn_exp2f(-1.44269504f * x));
; }
; __device__ __forceinline__ unsigned pk4_u8(float a, float b, float c, float d) {
;   const unsigned qa = (unsigned)__builtin_rintf(fminf(fmaxf(a, 0.f), 1.f) * 255.f);
;   const unsigned qb = (unsigned)__builtin_rintf(fminf(fmaxf(b, 0.f), 1.f) * 255.f);
;   const unsigned qc = (unsigned)__builtin_rintf(fminf(fmaxf(c, 0.f), 1.f) * 255.f);
;   const unsigned qd = (unsigned)__builtin_rintf(fminf(fmaxf(d, 0.f), 1.f) * 255.f);
;   return qa | (qb << 8) | (qc << 16) | (qd << 24);
; __device__ void phase6(const Params& p) {
;     ...
;     WAIT_L(0); BAR;
;     {
;       unsigned* park0 = reinterpret_cast<unsigned*>(g_smem + 32768) + tid_e;
;       unsigned* park1 = reinterpret_cast<unsigned*>(g_smem + 98304) + tid_e;
;       #pragma unroll
;       for (int bj = 0; bj < 2; ++bj)
;         #pragma unroll
;         for (int n = 0; n < 2; ++n)
;           #pragma unroll
;           for (int ai = 0; ai < 2; ++ai)
;             #pragma unroll
;             for (int m = 0; m < 4; ++m) {
;               const f32x4 v = acc[ai][bj][m][n];
;               const unsigned w8 = pk4_u8(sigm(v[0]), sigm(v[1]), sigm(v[2]), sigm(v[3]));
;               const int i = ((bj * 2 + n) * 2 + ai) * 4 + m;
;               if (i < 16) park0[i * 512] = w8; else park1[(i - 16) * 512] = w8;
;             }
.LBB0_774:
	s_or_b64 exec, exec, s[56:57]
	v_and_b32_e32 v244, 0xff, v194
	v_lshrrev_b32_e32 v245, 8, v194
	v_lshlrev_b32_e32 v245, 7, v245
	v_add_u32_e32 v244, s54, v244
	v_lshl_add_u32 v244, v244, 9, v245
	v_add_u32_e32 v244, 0x4800000, v244
	global_load_dword v252, v244, s[30:31]
	global_load_dword v253, v244, s[30:31] offset:256
	v_mul_f32_e32 v125, 0xbfb8aa3b, v125
	v_mul_f32_e32 v124, 0xbfb8aa3b, v124
	v_mul_f32_e32 v117, 0xbfb8aa3b, v117
	v_mul_f32_e32 v116, 0xbfb8aa3b, v116
	v_mul_f32_e32 v109, 0xbfb8aa3b, v109
	v_mul_f32_e32 v108, 0xbfb8aa3b, v108
	v_mul_f32_e32 v101, 0xbfb8aa3b, v101
	v_mul_f32_e32 v100, 0xbfb8aa3b, v100
	v_mul_f32_e32 v93, 0xbfb8aa3b, v93
	v_mul_f32_e32 v92, 0xbfb8aa3b, v92
	v_mul_f32_e32 v85, 0xbfb8aa3b, v85
	v_mul_f32_e32 v84, 0xbfb8aa3b, v84
	v_mul_f32_e32 v77, 0xbfb8aa3b, v77
	v_mul_f32_e32 v76, 0xbfb8aa3b, v76
	v_mul_f32_e32 v69, 0xbfb8aa3b, v69
	v_mul_f32_e32 v68, 0xbfb8aa3b, v68
	v_mul_f32_e32 v61, 0xbfb8aa3b, v61
	v_mul_f32_e32 v60, 0xbfb8aa3b, v60
	v_mul_f32_e32 v53, 0xbfb8aa3b, v53
	v_mul_f32_e32 v52, 0xbfb8aa3b, v52
	v_mul_f32_e32 v45, 0xbfb8aa3b, v45
	v_mul_f32_e32 v44, 0xbfb8aa3b, v44
	v_mul_f32_e32 v37, 0xbfb8aa3b, v37
	v_mul_f32_e32 v36, 0xbfb8aa3b, v36
	v_mul_f32_e32 v29, 0xbfb8aa3b, v29
	v_mul_f32_e32 v28, 0xbfb8aa3b, v28
	v_mul_f32_e32 v21, 0xbfb8aa3b, v21
	v_mul_f32_e32 v20, 0xbfb8aa3b, v20
	v_mul_f32_e32 v13, 0xbfb8aa3b, v13
	v_mul_f32_e32 v12, 0xbfb8aa3b, v12
	v_exp_f32_e32 v125, v125
	v_exp_f32_e32 v124, v124
	v_exp_f32_e32 v117, v117
	v_exp_f32_e32 v116, v116
	v_exp_f32_e32 v109, v109
	v_exp_f32_e32 v108, v108
	v_exp_f32_e32 v101, v101
	v_exp_f32_e32 v100, v100
	v_exp_f32_e32 v93, v93
	v_exp_f32_e32 v92, v92
	v_exp_f32_e32 v85, v85
	v_exp_f32_e32 v84, v84
	v_exp_f32_e32 v77, v77
	v_exp_f32_e32 v76, v76
	v_exp_f32_e32 v69, v69
	v_exp_f32_e32 v68, v68
	v_exp_f32_e32 v61, v61
	v_exp_f32_e32 v60, v60
	v_exp_f32_e32 v53, v53
	v_exp_f32_e32 v52, v52
	v_exp_f32_e32 v45, v45
	v_exp_f32_e32 v44, v44
	v_exp_f32_e32 v37, v37
	v_exp_f32_e32 v36, v36
	v_exp_f32_e32 v29, v29
	v_exp_f32_e32 v28, v28
	v_exp_f32_e32 v21, v21
	v_exp_f32_e32 v20, v20
	v_exp_f32_e32 v13, v13
	v_exp_f32_e32 v12, v12
	v_add_f32_e32 v125, 1.0, v125
	v_add_f32_e32 v124, 1.0, v124
	v_add_f32_e32 v117, 1.0, v117
	v_add_f32_e32 v116, 1.0, v116
	v_add_f32_e32 v109, 1.0, v109
	v_add_f32_e32 v108, 1.0, v108
	v_add_f32_e32 v101, 1.0, v101
	v_add_f32_e32 v100, 1.0, v100
	v_add_f32_e32 v93, 1.0, v93
	v_add_f32_e32 v92, 1.0, v92
	v_add_f32_e32 v85, 1.0, v85
	v_add_f32_e32 v84, 1.0, v84
	v_add_f32_e32 v77, 1.0, v77
	v_add_f32_e32 v76, 1.0, v76
	v_add_f32_e32 v69, 1.0, v69
	v_add_f32_e32 v68, 1.0, v68
	v_add_f32_e32 v61, 1.0, v61
	v_add_f32_e32 v60, 1.0, v60
	v_add_f32_e32 v53, 1.0, v53
	v_add_f32_e32 v52, 1.0, v52
	v_add_f32_e32 v45, 1.0, v45
	v_add_f32_e32 v44, 1.0, v44
	v_add_f32_e32 v37, 1.0, v37
	v_add_f32_e32 v36, 1.0, v36
	v_add_f32_e32 v29, 1.0, v29
	v_add_f32_e32 v28, 1.0, v28
	v_add_f32_e32 v21, 1.0, v21
	v_add_f32_e32 v20, 1.0, v20
	v_add_f32_e32 v13, 1.0, v13
	v_add_f32_e32 v12, 1.0, v12
	v_rcp_f32_e64 v125, v125 clamp
	v_rcp_f32_e64 v124, v124 clamp
	v_rcp_f32_e64 v117, v117 clamp
	v_rcp_f32_e64 v116, v116 clamp
	v_rcp_f32_e64 v109, v109 clamp
	v_rcp_f32_e64 v108, v108 clamp
	v_rcp_f32_e64 v101, v101 clamp
	v_rcp_f32_e64 v100, v100 clamp
	v_rcp_f32_e64 v93, v93 clamp
	v_rcp_f32_e64 v92, v92 clamp
	v_rcp_f32_e64 v85, v85 clamp
	v_rcp_f32_e64 v84, v84 clamp
	v_rcp_f32_e64 v77, v77 clamp
	v_rcp_f32_e64 v76, v76 clamp
	v_rcp_f32_e64 v69, v69 clamp
	v_rcp_f32_e64 v68, v68 clamp
	v_rcp_f32_e64 v61, v61 clamp
	v_rcp_f32_e64 v60, v60 clamp
	v_rcp_f32_e64 v53, v53 clamp
	v_rcp_f32_e64 v52, v52 clamp
	v_rcp_f32_e64 v45, v45 clamp
	v_rcp_f32_e64 v44, v44 clamp
	v_rcp_f32_e64 v37, v37 clamp
	v_rcp_f32_e64 v36, v36 clamp
	v_rcp_f32_e64 v29, v29 clamp
	v_rcp_f32_e64 v28, v28 clamp
	v_rcp_f32_e64 v21, v21 clamp
	v_rcp_f32_e64 v20, v20 clamp
	v_rcp_f32_e64 v13, v13 clamp
	v_rcp_f32_e64 v12, v12 clamp
	v_mul_f32_e32 v5, 0xbfb8aa3b, v5
	v_mul_f32_e32 v4, 0xbfb8aa3b, v4
	v_mul_f32_e32 v1, 0xbfb8aa3b, v1
	v_mul_f32_e32 v0, 0xbfb8aa3b, v0
	v_mul_f32_e32 v125, 0x437f0000, v125
	v_mul_f32_e32 v124, 0x437f0000, v124
	v_mul_f32_e32 v121, 0xbfb8aa3b, v121
	v_mul_f32_e32 v120, 0xbfb8aa3b, v120
	v_mul_f32_e32 v117, 0x437f0000, v117
	v_mul_f32_e32 v116, 0x437f0000, v116
	v_mul_f32_e32 v113, 0xbfb8aa3b, v113
	v_mul_f32_e32 v112, 0xbfb8aa3b, v112
	v_mul_f32_e32 v109, 0x437f0000, v109
	v_mul_f32_e32 v108, 0x437f0000, v108
	v_mul_f32_e32 v105, 0xbfb8aa3b, v105
	v_mul_f32_e32 v104, 0xbfb8aa3b, v104
	v_mul_f32_e32 v101, 0x437f0000, v101
	v_mul_f32_e32 v100, 0x437f0000, v100
	v_mul_f32_e32 v97, 0xbfb8aa3b, v97
	v_mul_f32_e32 v96, 0xbfb8aa3b, v96
	v_mul_f32_e32 v93, 0x437f0000, v93
	v_mul_f32_e32 v92, 0x437f0000, v92
	v_mul_f32_e32 v89, 0xbfb8aa3b, v89
	v_mul_f32_e32 v88, 0xbfb8aa3b, v88
	v_mul_f32_e32 v85, 0x437f0000, v85
	v_mul_f32_e32 v84, 0x437f0000, v84
	v_mul_f32_e32 v81, 0xbfb8aa3b, v81
	v_mul_f32_e32 v80, 0xbfb8aa3b, v80
	v_mul_f32_e32 v77, 0x437f0000, v77
	v_mul_f32_e32 v76, 0x437f0000, v76
	v_mul_f32_e32 v73, 0xbfb8aa3b, v73
	v_mul_f32_e32 v72, 0xbfb8aa3b, v72
	v_mul_f32_e32 v69, 0x437f0000, v69
	v_mul_f32_e32 v68, 0x437f0000, v68
	v_mul_f32_e32 v65, 0xbfb8aa3b, v65
	v_mul_f32_e32 v64, 0xbfb8aa3b, v64
	v_mul_f32_e32 v61, 0x437f0000, v61
	v_mul_f32_e32 v60, 0x437f0000, v60
	v_mul_f32_e32 v57, 0xbfb8aa3b, v57
	v_mul_f32_e32 v56, 0xbfb8aa3b, v56
	v_mul_f32_e32 v53, 0x437f0000, v53
	v_mul_f32_e32 v52, 0x437f0000, v52
	v_mul_f32_e32 v49, 0xbfb8aa3b, v49
	v_mul_f32_e32 v48, 0xbfb8aa3b, v48
	v_mul_f32_e32 v45, 0x437f0000, v45
	v_mul_f32_e32 v44, 0x437f0000, v44
; __device__ __forceinline__ float sigm(float x) {
;   return __builtin_amdgcn_rcpf(1.f + __builtin_amdgcn_exp2f(-1.44269504f * x));
; }
; __device__ __forceinline__ unsigned pk4_u8(float a, float b, float c, float d) {
;   const unsigned qa = (unsigned)__builtin_rintf(fminf(fmaxf(a, 0.f), 1.f) * 255.f);
;   const unsigned qb = (unsigned)__builtin_rintf(fminf(fmaxf(b, 0.f), 1.f) * 255.f);
;   const unsigned qc = (unsigned)__builtin_rintf(fminf(fmaxf(c, 0.f), 1.f) * 255.f);
;   const unsigned qd = (unsigned)__builtin_rintf(fminf(fmaxf(d, 0.f), 1.f) * 255.f);
;   return qa | (qb << 8) | (qc << 16) | (qd << 24);
; __device__ void phase6(const Params& p) {
;     ...
;             for (int m = 0; m < 4; ++m) {
;               const f32x4 v = acc[ai][bj][m][n];
;               const unsigned w8 = pk4_u8(sigm(v[0]), sigm(v[1]), sigm(v[2]), sigm(v[3]));
	v_mul_f32_e32 v41, 0xbfb8aa3b, v41
	v_mul_f32_e32 v40, 0xbfb8aa3b, v40
	v_mul_f32_e32 v37, 0x437f0000, v37
	v_mul_f32_e32 v36, 0x437f0000, v36
	v_mul_f32_e32 v33, 0xbfb8aa3b, v33
	v_mul_f32_e32 v32, 0xbfb8aa3b, v32
	v_mul_f32_e32 v29, 0x437f0000, v29
	v_mul_f32_e32 v28, 0x437f0000, v28
	v_mul_f32_e32 v25, 0xbfb8aa3b, v25
	v_mul_f32_e32 v24, 0xbfb8aa3b, v24
	v_mul_f32_e32 v21, 0x437f0000, v21
	v_mul_f32_e32 v20, 0x437f0000, v20
	v_mul_f32_e32 v17, 0xbfb8aa3b, v17
	v_mul_f32_e32 v16, 0xbfb8aa3b, v16
	v_mul_f32_e32 v13, 0x437f0000, v13
	v_mul_f32_e32 v12, 0x437f0000, v12
	v_mul_f32_e32 v9, 0xbfb8aa3b, v9
	v_mul_f32_e32 v8, 0xbfb8aa3b, v8
	v_exp_f32_e32 v5, v5
	v_exp_f32_e32 v4, v4
	v_mul_f32_e32 v6, 0xbfb8aa3b, v6
	v_mul_f32_e32 v7, 0xbfb8aa3b, v7
	v_exp_f32_e32 v1, v1
	v_exp_f32_e32 v0, v0
	v_mul_f32_e32 v2, 0xbfb8aa3b, v2
	v_mul_f32_e32 v3, 0xbfb8aa3b, v3
	v_rndne_f32_e32 v125, v125
	v_rndne_f32_e32 v124, v124
	v_mul_f32_e32 v126, 0xbfb8aa3b, v126
	v_mul_f32_e32 v127, 0xbfb8aa3b, v127
	v_exp_f32_e32 v121, v121
	v_exp_f32_e32 v120, v120
	v_mul_f32_e32 v122, 0xbfb8aa3b, v122
	v_mul_f32_e32 v123, 0xbfb8aa3b, v123
	v_rndne_f32_e32 v117, v117
	v_rndne_f32_e32 v116, v116
	v_mul_f32_e32 v118, 0xbfb8aa3b, v118
	v_mul_f32_e32 v119, 0xbfb8aa3b, v119
	v_exp_f32_e32 v113, v113
	v_exp_f32_e32 v112, v112
	v_mul_f32_e32 v114, 0xbfb8aa3b, v114
	v_mul_f32_e32 v115, 0xbfb8aa3b, v115
	v_rndne_f32_e32 v109, v109
	v_rndne_f32_e32 v108, v108
	v_mul_f32_e32 v110, 0xbfb8aa3b, v110
	v_mul_f32_e32 v111, 0xbfb8aa3b, v111
	v_exp_f32_e32 v105, v105
	v_exp_f32_e32 v104, v104
	v_mul_f32_e32 v106, 0xbfb8aa3b, v106
	v_mul_f32_e32 v107, 0xbfb8aa3b, v107
	v_rndne_f32_e32 v101, v101
	v_rndne_f32_e32 v100, v100
	v_mul_f32_e32 v102, 0xbfb8aa3b, v102
	v_mul_f32_e32 v103, 0xbfb8aa3b, v103
	v_exp_f32_e32 v97, v97
	v_exp_f32_e32 v96, v96
	v_mul_f32_e32 v98, 0xbfb8aa3b, v98
	v_mul_f32_e32 v99, 0xbfb8aa3b, v99
	v_rndne_f32_e32 v93, v93
	v_rndne_f32_e32 v92, v92
	v_mul_f32_e32 v94, 0xbfb8aa3b, v94
	v_mul_f32_e32 v95, 0xbfb8aa3b, v95
	v_exp_f32_e32 v89, v89
	v_exp_f32_e32 v88, v88
	v_mul_f32_e32 v90, 0xbfb8aa3b, v90
	v_mul_f32_e32 v91, 0xbfb8aa3b, v91
	v_rndne_f32_e32 v85, v85
	v_rndne_f32_e32 v84, v84
	v_mul_f32_e32 v86, 0xbfb8aa3b, v86
	v_mul_f32_e32 v87, 0xbfb8aa3b, v87
	v_exp_f32_e32 v81, v81
	v_exp_f32_e32 v80, v80
	v_mul_f32_e32 v82, 0xbfb8aa3b, v82
	v_mul_f32_e32 v83, 0xbfb8aa3b, v83
	v_rndne_f32_e32 v77, v77
	v_rndne_f32_e32 v76, v76
	v_mul_f32_e32 v78, 0xbfb8aa3b, v78
	v_mul_f32_e32 v79, 0xbfb8aa3b, v79
	v_exp_f32_e32 v73, v73
	v_exp_f32_e32 v72, v72
	v_mul_f32_e32 v74, 0xbfb8aa3b, v74
	v_mul_f32_e32 v75, 0xbfb8aa3b, v75
	v_rndne_f32_e32 v69, v69
	v_rndne_f32_e32 v68, v68
	v_mul_f32_e32 v70, 0xbfb8aa3b, v70
	v_mul_f32_e32 v71, 0xbfb8aa3b, v71
	v_exp_f32_e32 v65, v65
	v_exp_f32_e32 v64, v64
	v_mul_f32_e32 v66, 0xbfb8aa3b, v66
	v_mul_f32_e32 v67, 0xbfb8aa3b, v67
	v_rndne_f32_e32 v61, v61
	v_rndne_f32_e32 v60, v60
	v_mul_f32_e32 v62, 0xbfb8aa3b, v62
	v_mul_f32_e32 v63, 0xbfb8aa3b, v63
	v_exp_f32_e32 v57, v57
	v_exp_f32_e32 v56, v56
	v_mul_f32_e32 v58, 0xbfb8aa3b, v58
	v_mul_f32_e32 v59, 0xbfb8aa3b, v59
	v_rndne_f32_e32 v53, v53
	v_rndne_f32_e32 v52, v52
	v_mul_f32_e32 v54, 0xbfb8aa3b, v54
	v_mul_f32_e32 v55, 0xbfb8aa3b, v55
	v_exp_f32_e32 v49, v49
	v_exp_f32_e32 v48, v48
	v_mul_f32_e32 v50, 0xbfb8aa3b, v50
	v_mul_f32_e32 v51, 0xbfb8aa3b, v51
	v_rndne_f32_e32 v45, v45
	v_rndne_f32_e32 v44, v44
	v_mul_f32_e32 v46, 0xbfb8aa3b, v46
	v_mul_f32_e32 v47, 0xbfb8aa3b, v47
	v_exp_f32_e32 v41, v41
	v_exp_f32_e32 v40, v40
	v_mul_f32_e32 v42, 0xbfb8aa3b, v42
	v_mul_f32_e32 v43, 0xbfb8aa3b, v43
	v_rndne_f32_e32 v37, v37
	v_rndne_f32_e32 v36, v36
	v_mul_f32_e32 v38, 0xbfb8aa3b, v38
	v_mul_f32_e32 v39, 0xbfb8aa3b, v39
	v_exp_f32_e32 v33, v33
	v_exp_f32_e32 v32, v32
	v_mul_f32_e32 v34, 0xbfb8aa3b, v34
	v_mul_f32_e32 v35, 0xbfb8aa3b, v35
	v_rndne_f32_e32 v29, v29
	v_rndne_f32_e32 v28, v28
	v_mul_f32_e32 v30, 0xbfb8aa3b, v30
	v_mul_f32_e32 v31, 0xbfb8aa3b, v31
	v_exp_f32_e32 v25, v25
	v_exp_f32_e32 v24, v24
	v_mul_f32_e32 v26, 0xbfb8aa3b, v26
	v_mul_f32_e32 v27, 0xbfb8aa3b, v27
	v_rndne_f32_e32 v21, v21
	v_rndne_f32_e32 v20, v20
	v_mul_f32_e32 v22, 0xbfb8aa3b, v22
	v_mul_f32_e32 v23, 0xbfb8aa3b, v23
	v_exp_f32_e32 v17, v17
	v_exp_f32_e32 v16, v16
	v_mul_f32_e32 v18, 0xbfb8aa3b, v18
	v_mul_f32_e32 v19, 0xbfb8aa3b, v19
	v_rndne_f32_e32 v13, v13
	v_rndne_f32_e32 v12, v12
	v_mul_f32_e32 v14, 0xbfb8aa3b, v14
	v_mul_f32_e32 v15, 0xbfb8aa3b, v15
	v_exp_f32_e32 v9, v9
	v_exp_f32_e32 v8, v8
	v_mul_f32_e32 v10, 0xbfb8aa3b, v10
	v_mul_f32_e32 v11, 0xbfb8aa3b, v11
	v_exp_f32_e32 v6, v6
	v_exp_f32_e32 v7, v7
	v_exp_f32_e32 v2, v2
	v_exp_f32_e32 v3, v3
	v_cvt_u32_f32_e32 v125, v125
	v_exp_f32_e32 v126, v126
	v_cvt_u32_f32_e32 v124, v124
	v_exp_f32_e32 v127, v127
	v_exp_f32_e32 v122, v122
	v_exp_f32_e32 v123, v123
	v_cvt_u32_f32_e32 v117, v117
	v_exp_f32_e32 v118, v118
	v_cvt_u32_f32_e32 v116, v116
	v_exp_f32_e32 v119, v119
	v_exp_f32_e32 v114, v114
	v_exp_f32_e32 v115, v115
	v_cvt_u32_f32_e32 v109, v109
	v_exp_f32_e32 v110, v110
	v_cvt_u32_f32_e32 v108, v108
	v_exp_f32_e32 v111, v111
	v_exp_f32_e32 v106, v106
	v_exp_f32_e32 v107, v107
	v_cvt_u32_f32_e32 v101, v101
	v_exp_f32_e32 v102, v102
	v_cvt_u32_f32_e32 v100, v100
	v_exp_f32_e32 v103, v103
	v_exp_f32_e32 v98, v98
	v_exp_f32_e32 v99, v99
	v_cvt_u32_f32_e32 v93, v93
	v_exp_f32_e32 v94, v94
	v_cvt_u32_f32_e32 v92, v92
	v_exp_f32_e32 v95, v95
	v_exp_f32_e32 v90, v90
	v_exp_f32_e32 v91, v91
	v_cvt_u32_f32_e32 v85, v85
	v_exp_f32_e32 v86, v86
	v_cvt_u32_f32_e32 v84, v84
	v_exp_f32_e32 v87, v87
	v_exp_f32_e32 v82, v82
	v_exp_f32_e32 v83, v83
	v_cvt_u32_f32_e32 v77, v77
; __device__ __forceinline__ float sigm(float x) {
;   return __builtin_amdgcn_rcpf(1.f + __builtin_amdgcn_exp2f(-1.44269504f * x));
; }
; __device__ __forceinline__ unsigned pk4_u8(float a, float b, float c, float d) {
;   const unsigned qa = (unsigned)__builtin_rintf(fminf(fmaxf(a, 0.f), 1.f) * 255.f);
;   const unsigned qb = (unsigned)__builtin_rintf(fminf(fmaxf(b, 0.f), 1.f) * 255.f);
;   const unsigned qc = (unsigned)__builtin_rintf(fminf(fmaxf(c, 0.f), 1.f) * 255.f);
;   const unsigned qd = (unsigned)__builtin_rintf(fminf(fmaxf(d, 0.f), 1.f) * 255.f);
;   return qa | (qb << 8) | (qc << 16) | (qd << 24);
; __device__ void phase6(const Params& p) {
;     ...
;             for (int m = 0; m < 4; ++m) {
;               const f32x4 v = acc[ai][bj][m][n];
;               const unsigned w8 = pk4_u8(sigm(v[0]), sigm(v[1]), sigm(v[2]), sigm(v[3]));
	v_exp_f32_e32 v78, v78
	v_cvt_u32_f32_e32 v76, v76
	v_exp_f32_e32 v79, v79
	v_exp_f32_e32 v74, v74
	v_exp_f32_e32 v75, v75
	v_cvt_u32_f32_e32 v69, v69
	v_exp_f32_e32 v70, v70
	v_cvt_u32_f32_e32 v68, v68
	v_exp_f32_e32 v71, v71
	v_exp_f32_e32 v66, v66
	v_exp_f32_e32 v67, v67
	v_cvt_u32_f32_e32 v61, v61
	v_exp_f32_e32 v62, v62
	v_cvt_u32_f32_e32 v60, v60
	v_exp_f32_e32 v63, v63
	v_exp_f32_e32 v58, v58
	v_exp_f32_e32 v59, v59
	v_cvt_u32_f32_e32 v53, v53
	v_exp_f32_e32 v54, v54
	v_cvt_u32_f32_e32 v52, v52
	v_exp_f32_e32 v55, v55
	v_exp_f32_e32 v50, v50
	v_exp_f32_e32 v51, v51
	v_cvt_u32_f32_e32 v45, v45
	v_exp_f32_e32 v46, v46
	v_cvt_u32_f32_e32 v44, v44
	v_exp_f32_e32 v47, v47
	v_exp_f32_e32 v42, v42
	v_exp_f32_e32 v43, v43
	v_cvt_u32_f32_e32 v37, v37
	v_exp_f32_e32 v38, v38
	v_cvt_u32_f32_e32 v36, v36
	v_exp_f32_e32 v39, v39
	v_exp_f32_e32 v34, v34
	v_exp_f32_e32 v35, v35
	v_cvt_u32_f32_e32 v29, v29
	v_exp_f32_e32 v30, v30
	v_cvt_u32_f32_e32 v28, v28
	v_exp_f32_e32 v31, v31
	v_exp_f32_e32 v26, v26
	v_exp_f32_e32 v27, v27
	v_cvt_u32_f32_e32 v21, v21
	v_exp_f32_e32 v22, v22
	v_cvt_u32_f32_e32 v20, v20
	v_exp_f32_e32 v23, v23
	v_exp_f32_e32 v18, v18
	v_exp_f32_e32 v19, v19
	v_cvt_u32_f32_e32 v13, v13
	v_exp_f32_e32 v14, v14
	v_cvt_u32_f32_e32 v12, v12
	v_exp_f32_e32 v15, v15
	v_exp_f32_e32 v10, v10
	v_exp_f32_e32 v11, v11
	v_add_f32_e32 v5, 1.0, v5
	v_add_f32_e32 v4, 1.0, v4
	v_add_f32_e32 v1, 1.0, v1
	v_add_f32_e32 v0, 1.0, v0
	v_add_f32_e32 v121, 1.0, v121
	v_add_f32_e32 v120, 1.0, v120
	v_add_f32_e32 v113, 1.0, v113
	v_add_f32_e32 v112, 1.0, v112
	v_add_f32_e32 v105, 1.0, v105
	v_add_f32_e32 v104, 1.0, v104
	v_add_f32_e32 v97, 1.0, v97
	v_add_f32_e32 v96, 1.0, v96
	v_add_f32_e32 v89, 1.0, v89
	v_add_f32_e32 v88, 1.0, v88
	v_add_f32_e32 v81, 1.0, v81
	v_add_f32_e32 v80, 1.0, v80
	v_add_f32_e32 v73, 1.0, v73
	v_add_f32_e32 v72, 1.0, v72
	v_add_f32_e32 v65, 1.0, v65
	v_add_f32_e32 v64, 1.0, v64
	v_add_f32_e32 v57, 1.0, v57
	v_add_f32_e32 v56, 1.0, v56
	v_add_f32_e32 v49, 1.0, v49
	v_add_f32_e32 v48, 1.0, v48
	v_add_f32_e32 v41, 1.0, v41
	v_add_f32_e32 v40, 1.0, v40
	v_add_f32_e32 v33, 1.0, v33
	v_add_f32_e32 v32, 1.0, v32
	v_add_f32_e32 v25, 1.0, v25
	v_add_f32_e32 v24, 1.0, v24
	v_add_f32_e32 v17, 1.0, v17
	v_add_f32_e32 v16, 1.0, v16
	v_add_f32_e32 v9, 1.0, v9
	v_add_f32_e32 v8, 1.0, v8
	v_rcp_f32_e64 v5, v5 clamp
	v_rcp_f32_e64 v4, v4 clamp
	v_add_f32_e32 v6, 1.0, v6
	v_add_f32_e32 v7, 1.0, v7
	v_rcp_f32_e64 v1, v1 clamp
	v_rcp_f32_e64 v0, v0 clamp
	v_add_f32_e32 v2, 1.0, v2
	v_add_f32_e32 v3, 1.0, v3
	v_add_f32_e32 v126, 1.0, v126
	v_lshl_or_b32 v124, v125, 8, v124
	v_add_f32_e32 v125, 1.0, v127
	v_rcp_f32_e64 v121, v121 clamp
	v_rcp_f32_e64 v120, v120 clamp
	v_add_f32_e32 v122, 1.0, v122
	v_add_f32_e32 v123, 1.0, v123
	v_add_f32_e32 v118, 1.0, v118
	v_lshl_or_b32 v116, v117, 8, v116
	v_add_f32_e32 v117, 1.0, v119
	v_rcp_f32_e64 v113, v113 clamp
	v_rcp_f32_e64 v112, v112 clamp
	v_add_f32_e32 v114, 1.0, v114
	v_add_f32_e32 v115, 1.0, v115
	v_add_f32_e32 v110, 1.0, v110
	v_lshl_or_b32 v108, v109, 8, v108
	v_add_f32_e32 v109, 1.0, v111
	v_rcp_f32_e64 v105, v105 clamp
	v_rcp_f32_e64 v104, v104 clamp
	v_add_f32_e32 v106, 1.0, v106
	v_add_f32_e32 v107, 1.0, v107
	v_add_f32_e32 v102, 1.0, v102
	v_lshl_or_b32 v100, v101, 8, v100
	v_add_f32_e32 v101, 1.0, v103
	v_rcp_f32_e64 v97, v97 clamp
	v_rcp_f32_e64 v96, v96 clamp
	v_add_f32_e32 v98, 1.0, v98
	v_add_f32_e32 v99, 1.0, v99
	v_add_f32_e32 v94, 1.0, v94
	v_lshl_or_b32 v92, v93, 8, v92
	v_add_f32_e32 v93, 1.0, v95
	v_rcp_f32_e64 v89, v89 clamp
	v_rcp_f32_e64 v88, v88 clamp
	v_add_f32_e32 v90, 1.0, v90
	v_add_f32_e32 v91, 1.0, v91
	v_add_f32_e32 v86, 1.0, v86
	v_lshl_or_b32 v84, v85, 8, v84
	v_add_f32_e32 v85, 1.0, v87
	v_rcp_f32_e64 v81, v81 clamp
	v_rcp_f32_e64 v80, v80 clamp
	v_add_f32_e32 v82, 1.0, v82
	v_add_f32_e32 v83, 1.0, v83
	v_add_f32_e32 v78, 1.0, v78
	v_lshl_or_b32 v76, v77, 8, v76
	v_add_f32_e32 v77, 1.0, v79
	v_rcp_f32_e64 v73, v73 clamp
	v_rcp_f32_e64 v72, v72 clamp
	v_add_f32_e32 v74, 1.0, v74
	v_add_f32_e32 v75, 1.0, v75
	v_add_f32_e32 v70, 1.0, v70
	v_lshl_or_b32 v68, v69, 8, v68
	v_add_f32_e32 v69, 1.0, v71
	v_rcp_f32_e64 v65, v65 clamp
	v_rcp_f32_e64 v64, v64 clamp
	v_add_f32_e32 v66, 1.0, v66
	v_add_f32_e32 v67, 1.0, v67
	v_add_f32_e32 v62, 1.0, v62
	v_lshl_or_b32 v60, v61, 8, v60
	v_add_f32_e32 v61, 1.0, v63
	v_rcp_f32_e64 v57, v57 clamp
	v_rcp_f32_e64 v56, v56 clamp
	v_add_f32_e32 v58, 1.0, v58
	v_add_f32_e32 v59, 1.0, v59
	v_add_f32_e32 v54, 1.0, v54
	v_lshl_or_b32 v52, v53, 8, v52
	v_add_f32_e32 v53, 1.0, v55
	v_rcp_f32_e64 v49, v49 clamp
	v_rcp_f32_e64 v48, v48 clamp
	v_add_f32_e32 v50, 1.0, v50
	v_add_f32_e32 v51, 1.0, v51
	v_add_f32_e32 v46, 1.0, v46
	v_lshl_or_b32 v44, v45, 8, v44
	v_add_f32_e32 v45, 1.0, v47
	v_rcp_f32_e64 v41, v41 clamp
	v_rcp_f32_e64 v40, v40 clamp
	v_add_f32_e32 v42, 1.0, v42
	v_add_f32_e32 v43, 1.0, v43
	v_add_f32_e32 v38, 1.0, v38
	v_lshl_or_b32 v36, v37, 8, v36
	v_add_f32_e32 v37, 1.0, v39
	v_rcp_f32_e64 v33, v33 clamp
	v_rcp_f32_e64 v32, v32 clamp
	v_add_f32_e32 v34, 1.0, v34
	v_add_f32_e32 v35, 1.0, v35
	v_add_f32_e32 v30, 1.0, v30
	v_lshl_or_b32 v28, v29, 8, v28
	v_add_f32_e32 v29, 1.0, v31
	v_rcp_f32_e64 v25, v25 clamp
	v_rcp_f32_e64 v24, v24 clamp
	v_add_f32_e32 v26, 1.0, v26
	v_add_f32_e32 v27, 1.0, v27
	v_add_f32_e32 v22, 1.0, v22
	v_lshl_or_b32 v20, v21, 8, v20
	v_add_f32_e32 v21, 1.0, v23
	v_rcp_f32_e64 v17, v17 clamp
	v_rcp_f32_e64 v16, v16 clamp
	v_add_f32_e32 v18, 1.0, v18
	v_add_f32_e32 v19, 1.0, v19
	v_add_f32_e32 v14, 1.0, v14
	v_lshl_or_b32 v12, v13, 8, v12
	v_add_f32_e32 v13, 1.0, v15
	v_rcp_f32_e64 v9, v9 clamp
; __device__ __forceinline__ float sigm(float x) {
;   return __builtin_amdgcn_rcpf(1.f + __builtin_amdgcn_exp2f(-1.44269504f * x));
; }
; __device__ __forceinline__ unsigned pk4_u8(float a, float b, float c, float d) {
;   const unsigned qa = (unsigned)__builtin_rintf(fminf(fmaxf(a, 0.f), 1.f) * 255.f);
;   const unsigned qb = (unsigned)__builtin_rintf(fminf(fmaxf(b, 0.f), 1.f) * 255.f);
;   const unsigned qc = (unsigned)__builtin_rintf(fminf(fmaxf(c, 0.f), 1.f) * 255.f);
;   const unsigned qd = (unsigned)__builtin_rintf(fminf(fmaxf(d, 0.f), 1.f) * 255.f);
;   return qa | (qb << 8) | (qc << 16) | (qd << 24);
; __device__ void phase6(const Params& p) {
;     ...
;             for (int m = 0; m < 4; ++m) {
;               const f32x4 v = acc[ai][bj][m][n];
;               const unsigned w8 = pk4_u8(sigm(v[0]), sigm(v[1]), sigm(v[2]), sigm(v[3]));
	v_rcp_f32_e64 v8, v8 clamp
	v_add_f32_e32 v10, 1.0, v10
	v_add_f32_e32 v11, 1.0, v11
	v_rcp_f32_e64 v6, v6 clamp
	v_rcp_f32_e64 v7, v7 clamp
	v_rcp_f32_e64 v2, v2 clamp
	v_rcp_f32_e64 v3, v3 clamp
	v_rcp_f32_e64 v126, v126 clamp
	v_rcp_f32_e64 v125, v125 clamp
	v_rcp_f32_e64 v122, v122 clamp
	v_rcp_f32_e64 v123, v123 clamp
	v_rcp_f32_e64 v118, v118 clamp
	v_rcp_f32_e64 v117, v117 clamp
	v_rcp_f32_e64 v114, v114 clamp
	v_rcp_f32_e64 v115, v115 clamp
	v_rcp_f32_e64 v110, v110 clamp
	v_rcp_f32_e64 v109, v109 clamp
	v_rcp_f32_e64 v106, v106 clamp
	v_rcp_f32_e64 v107, v107 clamp
	v_rcp_f32_e64 v102, v102 clamp
	v_rcp_f32_e64 v101, v101 clamp
	v_rcp_f32_e64 v98, v98 clamp
	v_rcp_f32_e64 v99, v99 clamp
	v_rcp_f32_e64 v94, v94 clamp
	v_rcp_f32_e64 v93, v93 clamp
	v_rcp_f32_e64 v90, v90 clamp
	v_rcp_f32_e64 v91, v91 clamp
	v_rcp_f32_e64 v86, v86 clamp
	v_rcp_f32_e64 v85, v85 clamp
	v_rcp_f32_e64 v82, v82 clamp
	v_rcp_f32_e64 v83, v83 clamp
	v_rcp_f32_e64 v78, v78 clamp
	v_rcp_f32_e64 v77, v77 clamp
	v_rcp_f32_e64 v74, v74 clamp
	v_rcp_f32_e64 v75, v75 clamp
	v_rcp_f32_e64 v70, v70 clamp
	v_rcp_f32_e64 v69, v69 clamp
	v_rcp_f32_e64 v66, v66 clamp
	v_rcp_f32_e64 v67, v67 clamp
	v_rcp_f32_e64 v62, v62 clamp
	v_rcp_f32_e64 v61, v61 clamp
	v_rcp_f32_e64 v58, v58 clamp
	v_rcp_f32_e64 v59, v59 clamp
	v_rcp_f32_e64 v54, v54 clamp
	v_rcp_f32_e64 v53, v53 clamp
	v_rcp_f32_e64 v50, v50 clamp
	v_rcp_f32_e64 v51, v51 clamp
	v_rcp_f32_e64 v46, v46 clamp
	v_rcp_f32_e64 v45, v45 clamp
	v_rcp_f32_e64 v42, v42 clamp
	v_rcp_f32_e64 v43, v43 clamp
	v_rcp_f32_e64 v38, v38 clamp
	v_rcp_f32_e64 v37, v37 clamp
	v_rcp_f32_e64 v34, v34 clamp
	v_rcp_f32_e64 v35, v35 clamp
	v_rcp_f32_e64 v30, v30 clamp
	v_rcp_f32_e64 v29, v29 clamp
	v_rcp_f32_e64 v26, v26 clamp
	v_rcp_f32_e64 v27, v27 clamp
	v_rcp_f32_e64 v22, v22 clamp
	v_rcp_f32_e64 v21, v21 clamp
	v_rcp_f32_e64 v18, v18 clamp
	v_rcp_f32_e64 v19, v19 clamp
	v_rcp_f32_e64 v14, v14 clamp
	v_rcp_f32_e64 v13, v13 clamp
	v_rcp_f32_e64 v10, v10 clamp
	v_rcp_f32_e64 v11, v11 clamp
	v_mul_f32_e32 v5, 0x437f0000, v5
	v_mul_f32_e32 v4, 0x437f0000, v4
	v_mul_f32_e32 v1, 0x437f0000, v1
	v_mul_f32_e32 v0, 0x437f0000, v0
	v_mul_f32_e32 v121, 0x437f0000, v121
	v_mul_f32_e32 v120, 0x437f0000, v120
	v_mul_f32_e32 v113, 0x437f0000, v113
	v_mul_f32_e32 v112, 0x437f0000, v112
	v_mul_f32_e32 v105, 0x437f0000, v105
	v_mul_f32_e32 v104, 0x437f0000, v104
	v_mul_f32_e32 v97, 0x437f0000, v97
	v_mul_f32_e32 v96, 0x437f0000, v96
	v_mul_f32_e32 v89, 0x437f0000, v89
	v_mul_f32_e32 v88, 0x437f0000, v88
	v_mul_f32_e32 v81, 0x437f0000, v81
	v_mul_f32_e32 v80, 0x437f0000, v80
	v_mul_f32_e32 v73, 0x437f0000, v73
	v_mul_f32_e32 v72, 0x437f0000, v72
	v_mul_f32_e32 v65, 0x437f0000, v65
	v_mul_f32_e32 v64, 0x437f0000, v64
	v_mul_f32_e32 v57, 0x437f0000, v57
	v_mul_f32_e32 v56, 0x437f0000, v56
	v_mul_f32_e32 v49, 0x437f0000, v49
	v_mul_f32_e32 v48, 0x437f0000, v48
	v_mul_f32_e32 v41, 0x437f0000, v41
	v_mul_f32_e32 v40, 0x437f0000, v40
	v_mul_f32_e32 v33, 0x437f0000, v33
	v_mul_f32_e32 v32, 0x437f0000, v32
	v_mul_f32_e32 v25, 0x437f0000, v25
	v_mul_f32_e32 v24, 0x437f0000, v24
	v_mul_f32_e32 v17, 0x437f0000, v17
	v_mul_f32_e32 v16, 0x437f0000, v16
	v_mul_f32_e32 v9, 0x437f0000, v9
	v_mul_f32_e32 v8, 0x437f0000, v8
	v_rndne_f32_e32 v5, v5
	v_rndne_f32_e32 v4, v4
	v_mul_f32_e32 v6, 0x437f0000, v6
	v_mul_f32_e32 v7, 0x437f0000, v7
	v_rndne_f32_e32 v1, v1
	v_rndne_f32_e32 v0, v0
	v_mul_f32_e32 v2, 0x437f0000, v2
	v_mul_f32_e32 v3, 0x437f0000, v3
	v_mul_f32_e32 v126, 0x437f0000, v126
	v_mul_f32_e32 v125, 0x437f0000, v125
	v_rndne_f32_e32 v121, v121
	v_rndne_f32_e32 v120, v120
	v_mul_f32_e32 v122, 0x437f0000, v122
	v_mul_f32_e32 v123, 0x437f0000, v123
	v_mul_f32_e32 v118, 0x437f0000, v118
	v_mul_f32_e32 v117, 0x437f0000, v117
	v_rndne_f32_e32 v113, v113
	v_rndne_f32_e32 v112, v112
	v_mul_f32_e32 v114, 0x437f0000, v114
	v_mul_f32_e32 v115, 0x437f0000, v115
	v_mul_f32_e32 v110, 0x437f0000, v110
	v_mul_f32_e32 v109, 0x437f0000, v109
	v_rndne_f32_e32 v105, v105
	v_rndne_f32_e32 v104, v104
	v_mul_f32_e32 v106, 0x437f0000, v106
	v_mul_f32_e32 v107, 0x437f0000, v107
	v_mul_f32_e32 v102, 0x437f0000, v102
	v_mul_f32_e32 v101, 0x437f0000, v101
	v_rndne_f32_e32 v97, v97
	v_rndne_f32_e32 v96, v96
	v_mul_f32_e32 v98, 0x437f0000, v98
	v_mul_f32_e32 v99, 0x437f0000, v99
	v_mul_f32_e32 v94, 0x437f0000, v94
	v_mul_f32_e32 v93, 0x437f0000, v93
	v_rndne_f32_e32 v89, v89
	v_rndne_f32_e32 v88, v88
	v_mul_f32_e32 v90, 0x437f0000, v90
	v_mul_f32_e32 v91, 0x437f0000, v91
	v_mul_f32_e32 v86, 0x437f0000, v86
	v_mul_f32_e32 v85, 0x437f0000, v85
	v_rndne_f32_e32 v81, v81
	v_rndne_f32_e32 v80, v80
	v_mul_f32_e32 v82, 0x437f0000, v82
	v_mul_f32_e32 v83, 0x437f0000, v83
	v_mul_f32_e32 v78, 0x437f0000, v78
	v_mul_f32_e32 v77, 0x437f0000, v77
	v_rndne_f32_e32 v73, v73
	v_rndne_f32_e32 v72, v72
	v_mul_f32_e32 v74, 0x437f0000, v74
	v_mul_f32_e32 v75, 0x437f0000, v75
	v_mul_f32_e32 v70, 0x437f0000, v70
	v_mul_f32_e32 v69, 0x437f0000, v69
	v_rndne_f32_e32 v65, v65
	v_rndne_f32_e32 v64, v64
	v_mul_f32_e32 v66, 0x437f0000, v66
	v_mul_f32_e32 v67, 0x437f0000, v67
	v_mul_f32_e32 v62, 0x437f0000, v62
	v_mul_f32_e32 v61, 0x437f0000, v61
	v_rndne_f32_e32 v57, v57
	v_rndne_f32_e32 v56, v56
	v_mul_f32_e32 v58, 0x437f0000, v58
	v_mul_f32_e32 v59, 0x437f0000, v59
	v_mul_f32_e32 v54, 0x437f0000, v54
	v_mul_f32_e32 v53, 0x437f0000, v53
	v_rndne_f32_e32 v49, v49
	v_rndne_f32_e32 v48, v48
	v_mul_f32_e32 v50, 0x437f0000, v50
	v_mul_f32_e32 v51, 0x437f0000, v51
	v_mul_f32_e32 v46, 0x437f0000, v46
	v_mul_f32_e32 v45, 0x437f0000, v45
	v_rndne_f32_e32 v41, v41
	v_rndne_f32_e32 v40, v40
	v_mul_f32_e32 v42, 0x437f0000, v42
; __device__ __forceinline__ unsigned pk4_u8(float a, float b, float c, float d) {
;   const unsigned qa = (unsigned)__builtin_rintf(fminf(fmaxf(a, 0.f), 1.f) * 255.f);
;   const unsigned qb = (unsigned)__builtin_rintf(fminf(fmaxf(b, 0.f), 1.f) * 255.f);
;   const unsigned qc = (unsigned)__builtin_rintf(fminf(fmaxf(c, 0.f), 1.f) * 255.f);
;   const unsigned qd = (unsigned)__builtin_rintf(fminf(fmaxf(d, 0.f), 1.f) * 255.f);
;   return qa | (qb << 8) | (qc << 16) | (qd << 24);
; __device__ void phase6(const Params& p) {
;     ...
;             for (int m = 0; m < 4; ++m) {
;               const f32x4 v = acc[ai][bj][m][n];
;               const unsigned w8 = pk4_u8(sigm(v[0]), sigm(v[1]), sigm(v[2]), sigm(v[3]));
	v_mul_f32_e32 v43, 0x437f0000, v43
	v_mul_f32_e32 v38, 0x437f0000, v38
	v_mul_f32_e32 v37, 0x437f0000, v37
	v_rndne_f32_e32 v33, v33
	v_rndne_f32_e32 v32, v32
	v_mul_f32_e32 v34, 0x437f0000, v34
	v_mul_f32_e32 v35, 0x437f0000, v35
	v_mul_f32_e32 v30, 0x437f0000, v30
	v_mul_f32_e32 v29, 0x437f0000, v29
	v_rndne_f32_e32 v25, v25
	v_rndne_f32_e32 v24, v24
	v_mul_f32_e32 v26, 0x437f0000, v26
	v_mul_f32_e32 v27, 0x437f0000, v27
	v_mul_f32_e32 v22, 0x437f0000, v22
	v_mul_f32_e32 v21, 0x437f0000, v21
	v_rndne_f32_e32 v17, v17
	v_rndne_f32_e32 v16, v16
	v_mul_f32_e32 v18, 0x437f0000, v18
	v_mul_f32_e32 v19, 0x437f0000, v19
	v_mul_f32_e32 v14, 0x437f0000, v14
	v_mul_f32_e32 v13, 0x437f0000, v13
	v_rndne_f32_e32 v9, v9
	v_rndne_f32_e32 v8, v8
	v_mul_f32_e32 v10, 0x437f0000, v10
	v_mul_f32_e32 v11, 0x437f0000, v11
	v_cvt_u32_f32_e32 v5, v5
	v_cvt_u32_f32_e32 v4, v4
	v_rndne_f32_e32 v6, v6
	v_rndne_f32_e32 v7, v7
	v_cvt_u32_f32_e32 v1, v1
	v_cvt_u32_f32_e32 v0, v0
	v_rndne_f32_e32 v2, v2
	v_rndne_f32_e32 v3, v3
	v_rndne_f32_e32 v126, v126
	v_rndne_f32_e32 v125, v125
	v_cvt_u32_f32_e32 v121, v121
	v_cvt_u32_f32_e32 v120, v120
	v_rndne_f32_e32 v122, v122
	v_rndne_f32_e32 v123, v123
	v_rndne_f32_e32 v118, v118
	v_rndne_f32_e32 v117, v117
	v_cvt_u32_f32_e32 v113, v113
	v_cvt_u32_f32_e32 v112, v112
	v_rndne_f32_e32 v114, v114
	v_rndne_f32_e32 v115, v115
	v_rndne_f32_e32 v110, v110
	v_rndne_f32_e32 v109, v109
	v_cvt_u32_f32_e32 v105, v105
	v_cvt_u32_f32_e32 v104, v104
	v_rndne_f32_e32 v106, v106
	v_rndne_f32_e32 v107, v107
	v_rndne_f32_e32 v102, v102
	v_rndne_f32_e32 v101, v101
	v_cvt_u32_f32_e32 v97, v97
	v_cvt_u32_f32_e32 v96, v96
	v_rndne_f32_e32 v98, v98
	v_rndne_f32_e32 v99, v99
	v_rndne_f32_e32 v94, v94
	v_rndne_f32_e32 v93, v93
	v_cvt_u32_f32_e32 v89, v89
	v_cvt_u32_f32_e32 v88, v88
	v_rndne_f32_e32 v90, v90
	v_rndne_f32_e32 v91, v91
	v_rndne_f32_e32 v86, v86
	v_rndne_f32_e32 v85, v85
	v_cvt_u32_f32_e32 v81, v81
	v_cvt_u32_f32_e32 v80, v80
	v_rndne_f32_e32 v82, v82
	v_rndne_f32_e32 v83, v83
	v_rndne_f32_e32 v78, v78
	v_rndne_f32_e32 v77, v77
	v_cvt_u32_f32_e32 v73, v73
	v_cvt_u32_f32_e32 v72, v72
	v_rndne_f32_e32 v74, v74
	v_rndne_f32_e32 v75, v75
	v_rndne_f32_e32 v70, v70
	v_rndne_f32_e32 v69, v69
	v_cvt_u32_f32_e32 v65, v65
	v_cvt_u32_f32_e32 v64, v64
	v_rndne_f32_e32 v66, v66
	v_rndne_f32_e32 v67, v67
	v_rndne_f32_e32 v62, v62
	v_rndne_f32_e32 v61, v61
	v_cvt_u32_f32_e32 v57, v57
	v_cvt_u32_f32_e32 v56, v56
	v_rndne_f32_e32 v58, v58
	v_rndne_f32_e32 v59, v59
	v_rndne_f32_e32 v54, v54
	v_rndne_f32_e32 v53, v53
	v_cvt_u32_f32_e32 v49, v49
	v_cvt_u32_f32_e32 v48, v48
	v_rndne_f32_e32 v50, v50
	v_rndne_f32_e32 v51, v51
	v_rndne_f32_e32 v46, v46
	v_rndne_f32_e32 v45, v45
	v_cvt_u32_f32_e32 v41, v41
	v_cvt_u32_f32_e32 v40, v40
	v_rndne_f32_e32 v42, v42
	v_rndne_f32_e32 v43, v43
	v_rndne_f32_e32 v38, v38
	v_rndne_f32_e32 v37, v37
	v_cvt_u32_f32_e32 v33, v33
	v_cvt_u32_f32_e32 v32, v32
	v_rndne_f32_e32 v34, v34
	v_rndne_f32_e32 v35, v35
	v_rndne_f32_e32 v30, v30
	v_rndne_f32_e32 v29, v29
	v_cvt_u32_f32_e32 v25, v25
	v_cvt_u32_f32_e32 v24, v24
	v_rndne_f32_e32 v26, v26
	v_rndne_f32_e32 v27, v27
	v_rndne_f32_e32 v22, v22
	v_rndne_f32_e32 v21, v21
	v_cvt_u32_f32_e32 v17, v17
	v_cvt_u32_f32_e32 v16, v16
	v_rndne_f32_e32 v18, v18
	v_rndne_f32_e32 v19, v19
	v_rndne_f32_e32 v14, v14
	v_rndne_f32_e32 v13, v13
	v_cvt_u32_f32_e32 v9, v9
	v_cvt_u32_f32_e32 v8, v8
	v_rndne_f32_e32 v10, v10
	v_rndne_f32_e32 v11, v11
	v_cvt_u32_f32_sdwa v6, v6 dst_sel:WORD_1 dst_unused:UNUSED_PAD src0_sel:DWORD
	v_cvt_u32_f32_sdwa v7, v7 dst_sel:BYTE_3 dst_unused:UNUSED_PAD src0_sel:DWORD
	v_cvt_u32_f32_sdwa v2, v2 dst_sel:WORD_1 dst_unused:UNUSED_PAD src0_sel:DWORD
	v_cvt_u32_f32_sdwa v3, v3 dst_sel:BYTE_3 dst_unused:UNUSED_PAD src0_sel:DWORD
	v_cvt_u32_f32_sdwa v126, v126 dst_sel:WORD_1 dst_unused:UNUSED_PAD src0_sel:DWORD
	v_cvt_u32_f32_sdwa v125, v125 dst_sel:BYTE_3 dst_unused:UNUSED_PAD src0_sel:DWORD
	v_cvt_u32_f32_sdwa v122, v122 dst_sel:WORD_1 dst_unused:UNUSED_PAD src0_sel:DWORD
	v_cvt_u32_f32_sdwa v123, v123 dst_sel:BYTE_3 dst_unused:UNUSED_PAD src0_sel:DWORD
	v_cvt_u32_f32_sdwa v118, v118 dst_sel:WORD_1 dst_unused:UNUSED_PAD src0_sel:DWORD
	v_cvt_u32_f32_sdwa v117, v117 dst_sel:BYTE_3 dst_unused:UNUSED_PAD src0_sel:DWORD
	v_cvt_u32_f32_sdwa v114, v114 dst_sel:WORD_1 dst_unused:UNUSED_PAD src0_sel:DWORD
	v_cvt_u32_f32_sdwa v115, v115 dst_sel:BYTE_3 dst_unused:UNUSED_PAD src0_sel:DWORD
	v_cvt_u32_f32_sdwa v110, v110 dst_sel:WORD_1 dst_unused:UNUSED_PAD src0_sel:DWORD
	v_cvt_u32_f32_sdwa v109, v109 dst_sel:BYTE_3 dst_unused:UNUSED_PAD src0_sel:DWORD
	v_cvt_u32_f32_sdwa v106, v106 dst_sel:WORD_1 dst_unused:UNUSED_PAD src0_sel:DWORD
	v_cvt_u32_f32_sdwa v107, v107 dst_sel:BYTE_3 dst_unused:UNUSED_PAD src0_sel:DWORD
	v_cvt_u32_f32_sdwa v102, v102 dst_sel:WORD_1 dst_unused:UNUSED_PAD src0_sel:DWORD
	v_cvt_u32_f32_sdwa v101, v101 dst_sel:BYTE_3 dst_unused:UNUSED_PAD src0_sel:DWORD
	v_cvt_u32_f32_sdwa v98, v98 dst_sel:WORD_1 dst_unused:UNUSED_PAD src0_sel:DWORD
	v_cvt_u32_f32_sdwa v99, v99 dst_sel:BYTE_3 dst_unused:UNUSED_PAD src0_sel:DWORD
	v_cvt_u32_f32_sdwa v94, v94 dst_sel:WORD_1 dst_unused:UNUSED_PAD src0_sel:DWORD
	v_cvt_u32_f32_sdwa v93, v93 dst_sel:BYTE_3 dst_unused:UNUSED_PAD src0_sel:DWORD
	v_cvt_u32_f32_sdwa v90, v90 dst_sel:WORD_1 dst_unused:UNUSED_PAD src0_sel:DWORD
	v_cvt_u32_f32_sdwa v91, v91 dst_sel:BYTE_3 dst_unused:UNUSED_PAD src0_sel:DWORD
	v_cvt_u32_f32_sdwa v86, v86 dst_sel:WORD_1 dst_unused:UNUSED_PAD src0_sel:DWORD
	v_cvt_u32_f32_sdwa v85, v85 dst_sel:BYTE_3 dst_unused:UNUSED_PAD src0_sel:DWORD
	v_cvt_u32_f32_sdwa v82, v82 dst_sel:WORD_1 dst_unused:UNUSED_PAD src0_sel:DWORD
; __device__ void phase6(const Params& p) {
;     ...
;             #pragma unroll
;             for (int m = 0; m < 4; ++m) {
;               const f32x4 v = acc[ai][bj][m][n];
;               const unsigned w8 = pk4_u8(sigm(v[0]), sigm(v[1]), sigm(v[2]), sigm(v[3]));
;               const int i = ((bj * 2 + n) * 2 + ai) * 4 + m;
;               if (i < 16) park0[i * 512] = w8; else park1[(i - 16) * 512] = w8;
;             }
	v_cvt_u32_f32_sdwa v83, v83 dst_sel:BYTE_3 dst_unused:UNUSED_PAD src0_sel:DWORD
	v_cvt_u32_f32_sdwa v78, v78 dst_sel:WORD_1 dst_unused:UNUSED_PAD src0_sel:DWORD
	v_cvt_u32_f32_sdwa v77, v77 dst_sel:BYTE_3 dst_unused:UNUSED_PAD src0_sel:DWORD
	v_cvt_u32_f32_sdwa v74, v74 dst_sel:WORD_1 dst_unused:UNUSED_PAD src0_sel:DWORD
	v_cvt_u32_f32_sdwa v75, v75 dst_sel:BYTE_3 dst_unused:UNUSED_PAD src0_sel:DWORD
	v_cvt_u32_f32_sdwa v70, v70 dst_sel:WORD_1 dst_unused:UNUSED_PAD src0_sel:DWORD
	v_cvt_u32_f32_sdwa v69, v69 dst_sel:BYTE_3 dst_unused:UNUSED_PAD src0_sel:DWORD
	v_cvt_u32_f32_sdwa v66, v66 dst_sel:WORD_1 dst_unused:UNUSED_PAD src0_sel:DWORD
	v_cvt_u32_f32_sdwa v67, v67 dst_sel:BYTE_3 dst_unused:UNUSED_PAD src0_sel:DWORD
	v_cvt_u32_f32_sdwa v62, v62 dst_sel:WORD_1 dst_unused:UNUSED_PAD src0_sel:DWORD
	v_cvt_u32_f32_sdwa v61, v61 dst_sel:BYTE_3 dst_unused:UNUSED_PAD src0_sel:DWORD
	v_cvt_u32_f32_sdwa v58, v58 dst_sel:WORD_1 dst_unused:UNUSED_PAD src0_sel:DWORD
	v_cvt_u32_f32_sdwa v59, v59 dst_sel:BYTE_3 dst_unused:UNUSED_PAD src0_sel:DWORD
	v_cvt_u32_f32_sdwa v54, v54 dst_sel:WORD_1 dst_unused:UNUSED_PAD src0_sel:DWORD
	v_cvt_u32_f32_sdwa v53, v53 dst_sel:BYTE_3 dst_unused:UNUSED_PAD src0_sel:DWORD
	v_cvt_u32_f32_sdwa v50, v50 dst_sel:WORD_1 dst_unused:UNUSED_PAD src0_sel:DWORD
	v_cvt_u32_f32_sdwa v51, v51 dst_sel:BYTE_3 dst_unused:UNUSED_PAD src0_sel:DWORD
	v_cvt_u32_f32_sdwa v46, v46 dst_sel:WORD_1 dst_unused:UNUSED_PAD src0_sel:DWORD
	v_cvt_u32_f32_sdwa v45, v45 dst_sel:BYTE_3 dst_unused:UNUSED_PAD src0_sel:DWORD
	v_cvt_u32_f32_sdwa v42, v42 dst_sel:WORD_1 dst_unused:UNUSED_PAD src0_sel:DWORD
	v_cvt_u32_f32_sdwa v43, v43 dst_sel:BYTE_3 dst_unused:UNUSED_PAD src0_sel:DWORD
	v_cvt_u32_f32_sdwa v38, v38 dst_sel:WORD_1 dst_unused:UNUSED_PAD src0_sel:DWORD
	v_cvt_u32_f32_sdwa v37, v37 dst_sel:BYTE_3 dst_unused:UNUSED_PAD src0_sel:DWORD
	v_cvt_u32_f32_sdwa v34, v34 dst_sel:WORD_1 dst_unused:UNUSED_PAD src0_sel:DWORD
	v_cvt_u32_f32_sdwa v35, v35 dst_sel:BYTE_3 dst_unused:UNUSED_PAD src0_sel:DWORD
	v_cvt_u32_f32_sdwa v30, v30 dst_sel:WORD_1 dst_unused:UNUSED_PAD src0_sel:DWORD
	v_cvt_u32_f32_sdwa v29, v29 dst_sel:BYTE_3 dst_unused:UNUSED_PAD src0_sel:DWORD
	v_cvt_u32_f32_sdwa v26, v26 dst_sel:WORD_1 dst_unused:UNUSED_PAD src0_sel:DWORD
	v_cvt_u32_f32_sdwa v27, v27 dst_sel:BYTE_3 dst_unused:UNUSED_PAD src0_sel:DWORD
	v_cvt_u32_f32_sdwa v22, v22 dst_sel:WORD_1 dst_unused:UNUSED_PAD src0_sel:DWORD
	v_cvt_u32_f32_sdwa v21, v21 dst_sel:BYTE_3 dst_unused:UNUSED_PAD src0_sel:DWORD
	v_cvt_u32_f32_sdwa v18, v18 dst_sel:WORD_1 dst_unused:UNUSED_PAD src0_sel:DWORD
	v_cvt_u32_f32_sdwa v19, v19 dst_sel:BYTE_3 dst_unused:UNUSED_PAD src0_sel:DWORD
	v_cvt_u32_f32_sdwa v14, v14 dst_sel:WORD_1 dst_unused:UNUSED_PAD src0_sel:DWORD
	v_cvt_u32_f32_sdwa v13, v13 dst_sel:BYTE_3 dst_unused:UNUSED_PAD src0_sel:DWORD
	v_cvt_u32_f32_sdwa v10, v10 dst_sel:WORD_1 dst_unused:UNUSED_PAD src0_sel:DWORD
	v_cvt_u32_f32_sdwa v11, v11 dst_sel:BYTE_3 dst_unused:UNUSED_PAD src0_sel:DWORD
	v_lshlrev_b32_e32 v139, 2, v142
	v_lshl_or_b32 v4, v5, 8, v4
	v_lshl_or_b32 v0, v1, 8, v0
	v_add_u32_e32 v138, 0x18000, v139
	v_lshl_or_b32 v120, v121, 8, v120
	v_lshl_or_b32 v112, v113, 8, v112
	v_lshl_or_b32 v104, v105, 8, v104
	v_lshl_or_b32 v96, v97, 8, v96
	v_lshl_or_b32 v88, v89, 8, v88
	v_lshl_or_b32 v80, v81, 8, v80
	v_lshl_or_b32 v72, v73, 8, v72
	v_lshl_or_b32 v64, v65, 8, v64
	v_lshl_or_b32 v56, v57, 8, v56
	v_lshl_or_b32 v48, v49, 8, v48
	v_lshl_or_b32 v40, v41, 8, v40
	v_lshl_or_b32 v32, v33, 8, v32
	v_lshl_or_b32 v24, v25, 8, v24
	v_lshl_or_b32 v16, v17, 8, v16
	v_lshl_or_b32 v8, v9, 8, v8
	v_or3_b32 v4, v4, v6, v7
	v_or3_b32 v0, v0, v2, v3
	s_waitcnt lgkmcnt(0)
	s_barrier
	v_or3_b32 v124, v124, v126, v125
	v_or3_b32 v120, v120, v122, v123
	v_or3_b32 v116, v116, v118, v117
	v_or3_b32 v112, v112, v114, v115
	v_or3_b32 v108, v108, v110, v109
	v_or3_b32 v104, v104, v106, v107
	v_or3_b32 v100, v100, v102, v101
	v_or3_b32 v96, v96, v98, v99
	v_or3_b32 v92, v92, v94, v93
	v_or3_b32 v88, v88, v90, v91
	v_or3_b32 v84, v84, v86, v85
	v_or3_b32 v80, v80, v82, v83
	v_or3_b32 v76, v76, v78, v77
	v_or3_b32 v72, v72, v74, v75
	v_or3_b32 v68, v68, v70, v69
	v_or3_b32 v64, v64, v66, v67
	v_or3_b32 v60, v60, v62, v61
	v_or3_b32 v56, v56, v58, v59
	v_or3_b32 v52, v52, v54, v53
	v_or3_b32 v48, v48, v50, v51
	v_or3_b32 v44, v44, v46, v45
	v_or3_b32 v40, v40, v42, v43
	v_or3_b32 v36, v36, v38, v37
	v_or3_b32 v32, v32, v34, v35
	v_or3_b32 v28, v28, v30, v29
	v_or3_b32 v24, v24, v26, v27
	v_or3_b32 v20, v20, v22, v21
	v_or3_b32 v16, v16, v18, v19
	v_or3_b32 v12, v12, v14, v13
	v_or3_b32 v8, v8, v10, v11
	ds_write2st64_b32 v138, v4, v0 offset0:112 offset1:120
	v_mov_b32_e32 v0, v194
	ds_write2st64_b32 v139, v124, v120 offset0:128 offset1:136
	ds_write2st64_b32 v139, v116, v112 offset0:144 offset1:152
	ds_write2st64_b32 v139, v108, v104 offset0:160 offset1:168
	ds_write2st64_b32 v139, v100, v96 offset0:176 offset1:184
	ds_write2st64_b32 v139, v92, v88 offset0:192 offset1:200
	ds_write2st64_b32 v139, v84, v80 offset0:208 offset1:216
	ds_write2st64_b32 v139, v76, v72 offset0:224 offset1:232
	ds_write2st64_b32 v139, v68, v64 offset0:240 offset1:248
	ds_write2st64_b32 v138, v60, v56 offset1:8
	ds_write2st64_b32 v138, v52, v48 offset0:16 offset1:24
	ds_write2st64_b32 v138, v44, v40 offset0:32 offset1:40
	ds_write2st64_b32 v138, v36, v32 offset0:48 offset1:56
	ds_write2st64_b32 v138, v28, v24 offset0:64 offset1:72
	ds_write2st64_b32 v138, v20, v16 offset0:80 offset1:88
	ds_write2st64_b32 v138, v12, v8 offset0:96 offset1:104
	s_lshl_b64 s[56:57], s[54:55], 9
	v_bfe_i32 v6, v0, 27, 1
	v_lshlrev_b32_e32 v4, 4, v0
; __device__ __forceinline__ int otid() { int t = threadIdx.x; asm volatile("" : "+v"(t)); return t; }
; __device__ __forceinline__ void gemm_small(const u16* __restrict__ A, const u16* __restrict__ Bt, const int K,
;                                            const int brow, const int bcol, f32x4 (&acc)[2][2][4][2]) {
;   u16* shm = reinterpret_cast<u16*>(g_smem);
;   const int tidx = otid();
;   const int wid = tidx >> 6, lane = tidx & 63, wr = wid >> 2, wc = wid & 3, fr = lane & 15, fq = lane >> 4;
;   #pragma unroll
;   for (int a = 0; a < 2; ++a)
;     #pragma unroll
;     for (int b = 0; b < 2; ++b)
;       #pragma unroll
;       for (int m = 0; m < 4; ++m)
;         #pragma unroll
;         for (int n = 0; n < 2; ++n) acc[a][b][m][n] = f32x4{0.f, 0.f, 0.f, 0.f};
;   bf16x8 At[4][2], B0[2][2], B1[2][2];
;   const unsigned ldsw = (unsigned)__builtin_amdgcn_readfirstlane(wid) * 1024u;
;   unsigned vo0, vo1;
;   {
;     int r0, c0, r1, c1;
;     stage_rc(tidx * 16, r0, c0);
;     stage_rc(tidx * 16 + 8192, r1, c1);
;     vo0 = (unsigned)(r0 * K + c0) * 2u;
;     vo1 = (unsigned)(r1 * K + c1) * 2u;
;   }
;   const int nt = K / BK;
	v_lshrrev_b32_e32 v6, 22, v6
	v_add_u32_e32 v6, v4, v6
	v_and_b32_e32 v6, 0xfffffc00, v6
	v_sub_u32_e32 v6, v4, v6
	v_lshrrev_b32_e32 v7, 4, v6
	v_bitop3_b32 v7, v7, v6, 32 bitop3:0x6c
	v_ashrrev_i32_e32 v6, 31, v6
	v_lshrrev_b32_e32 v6, 26, v6
	v_add_u32_e32 v6, v7, v6
	v_ashrrev_i32_e32 v6, 6, v6
	v_mul_i32_i24_e32 v8, 64, v6
	v_add_u32_e32 v4, 0x2000, v4
	v_sub_u32_e32 v7, v7, v8
	v_ashrrev_i32_e32 v8, 31, v4
	v_lshrrev_b32_e32 v8, 22, v8
	v_add_u32_e32 v8, v4, v8
	v_ashrrev_i32_e32 v8, 10, v8
	v_mul_i32_i24_e32 v9, 0x400, v8
	v_sub_u32_e32 v4, v4, v9
	v_lshrrev_b32_e32 v9, 4, v4
	v_bitop3_b32 v4, v9, v4, 32 bitop3:0x6c
	v_ashrrev_i32_e32 v9, 31, v4
	v_lshrrev_b32_e32 v9, 26, v9
	v_ashrrev_i32_e32 v1, 6, v0
	v_add_u32_e32 v9, v4, v9
	v_and_b32_e32 v2, 15, v0
	v_readfirstlane_b32 s24, v1
	v_ashrrev_i32_e32 v5, 31, v0
	v_and_b32_e32 v10, 0xc0, v9
	v_lshlrev_b32_e32 v1, 12, v1
	v_lshlrev_b32_e32 v11, 2, v0
	v_and_b32_e32 v3, 48, v0
	v_lshrrev_b32_e32 v5, 26, v5
	v_sub_u32_e32 v4, v4, v10
	v_and_b32_e32 v10, 0x3000, v1
	v_lshlrev_b32_e32 v1, 6, v2
	v_and_b32_e32 v11, 32, v11
	v_add_u32_e32 v5, v0, v5
	v_or_b32_e32 v2, v1, v3
	v_bitop3_b32 v12, v1, v11, v3 bitop3:0x36
	v_lshlrev_b32_e32 v1, 5, v0
	v_lshlrev_b32_e32 v0, 6, v0
	v_and_b32_e32 v0, 0x3c0, v0
	v_bitop3_b32 v3, v0, v11, v3 bitop3:0x36
	v_lshlrev_b32_e32 v0, 6, v5
	v_and_b32_e32 v0, 0xffffe000, v0
	v_ashrrev_i16_sdwa v7, v141, sext(v7) dst_sel:DWORD dst_unused:UNUSED_PAD src0_sel:DWORD src1_sel:BYTE_0
	v_lshl_add_u32 v0, v6, 9, v0
	v_bfe_i32 v7, v7, 0, 16
	v_and_or_b32 v0, v5, 64, v0
	v_and_b32_e32 v14, 0xffffe000, v1
	v_lshl_add_u32 v128, v7, 1, v0
	v_lshlrev_b32_e32 v0, 12, v8
	v_lshlrev_b32_e32 v1, 3, v9
	v_and_b32_e32 v0, 0xffffe000, v0
	v_and_b32_e32 v1, 0xfffffe00, v1
	s_lshl_b32 s24, s24, 10
	v_ashrrev_i16_sdwa v4, v141, sext(v4) dst_sel:DWORD dst_unused:UNUSED_PAD src0_sel:DWORD src1_sel:BYTE_0
	s_lshl_b64 s[58:59], s[52:53], 9
	v_add_u32_e32 v0, v0, v1
	v_lshlrev_b32_e32 v1, 6, v8
	v_bfe_i32 v4, v4, 0, 16
	s_add_u32 s56, s30, s56
	v_and_or_b32 v0, v1, 64, v0
	s_addc_u32 s57, s31, s57
	v_lshl_add_u32 v0, v4, 1, v0
	v_mov_b32_e32 v1, v129
	v_lshl_add_u64 v[130:131], s[56:57], 0, v[128:129]
	v_lshl_add_u64 v[132:133], s[56:57], 0, v[0:1]
	s_add_u32 s56, s30, s58
	s_addc_u32 s57, s31, s59
	v_bitop3_b32 v13, v2, s73, v11 bitop3:0xde
	v_bitop3_b32 v2, v2, s76, v11 bitop3:0xde
	v_or_b32_e32 v11, 0x800, v14
	v_or_b32_e32 v15, 0x1000, v14
	v_or_b32_e32 v16, 0x1800, v14
	v_lshl_add_u64 v[136:137], s[56:57], 0, v[0:1]
	v_mov_b32_e32 v0, 0
	v_lshl_add_u64 v[134:135], s[56:57], 0, v[128:129]
	s_mov_b64 s[56:57], 0
	v_add_u32_e32 v128, v13, v10
	v_add_u32_e32 v143, v12, v14
	v_add_u32_e32 v144, v3, v11
	v_add_u32_e32 v145, v3, v15
	v_add_u32_e32 v146, v3, v16
	v_add_u32_e32 v147, v2, v10
	v_mov_b32_e32 v1, v0
	v_mov_b32_e32 v2, v0
	v_mov_b32_e32 v3, v0
	v_mov_b32_e32 v32, v0
	v_mov_b32_e32 v33, v0
	v_mov_b32_e32 v34, v0
	v_mov_b32_e32 v35, v0
	v_mov_b32_e32 v4, v0
	v_mov_b32_e32 v5, v0
	v_mov_b32_e32 v6, v0
	v_mov_b32_e32 v7, v0
	v_mov_b32_e32 v36, v0
	v_mov_b32_e32 v37, v0
	v_mov_b32_e32 v38, v0
	v_mov_b32_e32 v39, v0
	v_mov_b32_e32 v8, v0
	v_mov_b32_e32 v9, v0
	v_mov_b32_e32 v10, v0
	v_mov_b32_e32 v11, v0
	v_mov_b32_e32 v40, v0
	v_mov_b32_e32 v41, v0
	v_mov_b32_e32 v42, v0
	v_mov_b32_e32 v43, v0
	v_mov_b32_e32 v12, v0
	v_mov_b32_e32 v13, v0
	v_mov_b32_e32 v14, v0
	v_mov_b32_e32 v15, v0
	v_mov_b32_e32 v44, v0
	v_mov_b32_e32 v45, v0
	v_mov_b32_e32 v46, v0
	v_mov_b32_e32 v47, v0
	v_mov_b32_e32 v64, v0
	v_mov_b32_e32 v65, v0
	v_mov_b32_e32 v66, v0
	v_mov_b32_e32 v67, v0
	v_mov_b32_e32 v96, v0
	v_mov_b32_e32 v97, v0
	v_mov_b32_e32 v98, v0
	v_mov_b32_e32 v99, v0
	v_mov_b32_e32 v68, v0
	v_mov_b32_e32 v69, v0
	v_mov_b32_e32 v70, v0
	v_mov_b32_e32 v71, v0
	v_mov_b32_e32 v100, v0
	v_mov_b32_e32 v101, v0
	v_mov_b32_e32 v102, v0
	v_mov_b32_e32 v103, v0
	v_mov_b32_e32 v72, v0
	v_mov_b32_e32 v73, v0
	v_mov_b32_e32 v74, v0
	v_mov_b32_e32 v75, v0
	v_mov_b32_e32 v104, v0
	v_mov_b32_e32 v105, v0
	v_mov_b32_e32 v106, v0
	v_mov_b32_e32 v107, v0
	v_mov_b32_e32 v76, v0
	v_mov_b32_e32 v77, v0
	v_mov_b32_e32 v78, v0
	v_mov_b32_e32 v79, v0
	v_mov_b32_e32 v108, v0
	v_mov_b32_e32 v109, v0
	v_mov_b32_e32 v110, v0
	v_mov_b32_e32 v111, v0
	v_mov_b32_e32 v16, v0
	v_mov_b32_e32 v17, v0
	v_mov_b32_e32 v18, v0
	v_mov_b32_e32 v19, v0
	v_mov_b32_e32 v48, v0
	v_mov_b32_e32 v49, v0
	v_mov_b32_e32 v50, v0
	v_mov_b32_e32 v51, v0
	v_mov_b32_e32 v20, v0
	v_mov_b32_e32 v21, v0
	v_mov_b32_e32 v22, v0
	v_mov_b32_e32 v23, v0
	v_mov_b32_e32 v52, v0
	v_mov_b32_e32 v53, v0
	v_mov_b32_e32 v54, v0
	v_mov_b32_e32 v55, v0
	v_mov_b32_e32 v24, v0
	v_mov_b32_e32 v25, v0
	v_mov_b32_e32 v26, v0
	v_mov_b32_e32 v27, v0
	v_mov_b32_e32 v56, v0
	v_mov_b32_e32 v57, v0
	v_mov_b32_e32 v58, v0
	v_mov_b32_e32 v59, v0
	v_mov_b32_e32 v28, v0
	v_mov_b32_e32 v29, v0
	v_mov_b32_e32 v30, v0
	v_mov_b32_e32 v31, v0
	v_mov_b32_e32 v60, v0
	v_mov_b32_e32 v61, v0
	v_mov_b32_e32 v62, v0
	v_mov_b32_e32 v63, v0
	v_mov_b32_e32 v80, v0
	v_mov_b32_e32 v81, v0
	v_mov_b32_e32 v82, v0
	v_mov_b32_e32 v83, v0
	v_mov_b32_e32 v112, v0
	v_mov_b32_e32 v113, v0
	v_mov_b32_e32 v114, v0
	v_mov_b32_e32 v115, v0
	v_mov_b32_e32 v84, v0
	v_mov_b32_e32 v85, v0
	v_mov_b32_e32 v86, v0
	v_mov_b32_e32 v87, v0
	v_mov_b32_e32 v116, v0
	v_mov_b32_e32 v117, v0
	v_mov_b32_e32 v118, v0
	v_mov_b32_e32 v119, v0
	v_mov_b32_e32 v88, v0
	v_mov_b32_e32 v89, v0
	v_mov_b32_e32 v90, v0
	v_mov_b32_e32 v91, v0
	v_mov_b32_e32 v120, v0
	v_mov_b32_e32 v121, v0
	v_mov_b32_e32 v122, v0
	v_mov_b32_e32 v123, v0
	v_mov_b32_e32 v92, v0
	v_mov_b32_e32 v93, v0
	v_mov_b32_e32 v94, v0
	v_mov_b32_e32 v95, v0
	v_mov_b32_e32 v124, v0
	v_mov_b32_e32 v125, v0
	v_mov_b32_e32 v126, v0
	v_mov_b32_e32 v127, v0
